# add: mod GEMV weight loads kept 56 deep in flight (was one round trip per 4 k)
# speedup vs baseline: 1.0202x; 1.0025x over previous
; DI void mod_item(const KP& P, int l, int nc, LAS float* S  , LAS float* red  ) {
;     ...
;     __syncthreads();
;     const int col = tid % 48, kq = tid / 48, n0 = nc * 48;
;     if (kq < 8) {
;         float a[9];
; #pragma unroll
;         for (int r = 0; r < 9; ++r) a[r] = 0.f;
;         const float* w = P.w_mod + (size_t)l * D * 6144 + n0 + col;
; #pragma unroll 4
;         for (int k = kq * 128; k < kq * 128 + 128; ++k) { const float wv = w[(size_t)k * 6144];
; #pragma unroll
;             for (int r = 0; r < 9; ++r) a[r] += S[r * D + k] * wv; }
.LBB0_25:
	s_or_b64 exec, exec, s[16:17]
	v_mul_hi_i32 v2, v4, s35
	v_lshrrev_b32_e32 v5, 31, v2
	v_ashrrev_i32_e32 v2, 3, v2
	v_add_u32_e32 v2, v2, v5
	v_mul_lo_u32 v5, v2, 48
	v_sub_u32_e32 v6, v4, v5
	s_ashr_i32 s8, s44, 7
	v_cmp_gt_i32_e32 vcc, s36, v4
	v_ashrrev_i32_e32 v7, 31, v6
	s_waitcnt lgkmcnt(0)
	s_barrier
	s_and_saveexec_b64 s[4:5], vcc
	s_cbranch_execz .LBB0_29
	s_and_b32 s6, s43, 0x7f
	v_lshlrev_b32_e32 v5, 7, v2
	s_load_dwordx16 s[48:63], s[0:1], 0x0
	s_mul_i32 s9, s6, 0xc0
	v_mad_i64_i32 v[8:9], s[6:7], v5, s38, 0
	v_mad_i64_i32 v[8:9], s[6:7], s8, v19, v[8:9]
	v_or_b32_e32 v8, s9, v8
	v_lshl_add_u64 v[8:9], v[6:7], 2, v[8:9]
	v_mov_b32_e32 v10, 0
	s_waitcnt lgkmcnt(0)
	v_lshl_add_u64 v[8:9], s[56:57], 0, v[8:9]
	v_lshl_add_u32 v5, v2, 9, 0
	s_mov_b64 s[6:7], 0
	v_mov_b32_e32 v11, v10
	v_mov_b32_e32 v12, v10
	v_mov_b32_e32 v13, v10
	v_mov_b32_e32 v16, v10
	v_mov_b32_e32 v17, v10
	v_mov_b32_e32 v14, v10
	v_mov_b32_e32 v15, v10
	v_mov_b32_e32 v20, v10
	s_mov_b32 s46, 0x6000
	s_mov_b32 s47, 0
	v_mov_b32_e32 v238, v8
	v_mov_b32_e32 v239, v9
	global_load_dword v108, v[238:239], off
	v_lshl_add_u64 v[238:239], v[238:239], 0, s[46:47]
	global_load_dword v110, v[238:239], off
	v_lshl_add_u64 v[238:239], v[238:239], 0, s[46:47]
	global_load_dword v112, v[238:239], off
	v_lshl_add_u64 v[238:239], v[238:239], 0, s[46:47]
	global_load_dword v114, v[238:239], off
	v_lshl_add_u64 v[238:239], v[238:239], 0, s[46:47]
	global_load_dword v116, v[238:239], off
	v_lshl_add_u64 v[238:239], v[238:239], 0, s[46:47]
	global_load_dword v118, v[238:239], off
	v_lshl_add_u64 v[238:239], v[238:239], 0, s[46:47]
	global_load_dword v120, v[238:239], off
	v_lshl_add_u64 v[238:239], v[238:239], 0, s[46:47]
	global_load_dword v122, v[238:239], off
	v_lshl_add_u64 v[238:239], v[238:239], 0, s[46:47]
	global_load_dword v124, v[238:239], off
	v_lshl_add_u64 v[238:239], v[238:239], 0, s[46:47]
	global_load_dword v126, v[238:239], off
	v_lshl_add_u64 v[238:239], v[238:239], 0, s[46:47]
	global_load_dword v128, v[238:239], off
	v_lshl_add_u64 v[238:239], v[238:239], 0, s[46:47]
	global_load_dword v130, v[238:239], off
	v_lshl_add_u64 v[238:239], v[238:239], 0, s[46:47]
	global_load_dword v132, v[238:239], off
	v_lshl_add_u64 v[238:239], v[238:239], 0, s[46:47]
	global_load_dword v134, v[238:239], off
	v_lshl_add_u64 v[238:239], v[238:239], 0, s[46:47]
	global_load_dword v136, v[238:239], off
	v_lshl_add_u64 v[238:239], v[238:239], 0, s[46:47]
	global_load_dword v138, v[238:239], off
	v_lshl_add_u64 v[238:239], v[238:239], 0, s[46:47]
	global_load_dword v146, v[238:239], off
	v_lshl_add_u64 v[238:239], v[238:239], 0, s[46:47]
	global_load_dword v148, v[238:239], off
	v_lshl_add_u64 v[238:239], v[238:239], 0, s[46:47]
	global_load_dword v150, v[238:239], off
	v_lshl_add_u64 v[238:239], v[238:239], 0, s[46:47]
	global_load_dword v152, v[238:239], off
	v_lshl_add_u64 v[238:239], v[238:239], 0, s[46:47]
	global_load_dword v154, v[238:239], off
	v_lshl_add_u64 v[238:239], v[238:239], 0, s[46:47]
	global_load_dword v156, v[238:239], off
	v_lshl_add_u64 v[238:239], v[238:239], 0, s[46:47]
	global_load_dword v158, v[238:239], off
	v_lshl_add_u64 v[238:239], v[238:239], 0, s[46:47]
	global_load_dword v160, v[238:239], off
	v_lshl_add_u64 v[238:239], v[238:239], 0, s[46:47]
	global_load_dword v162, v[238:239], off
	v_lshl_add_u64 v[238:239], v[238:239], 0, s[46:47]
	global_load_dword v164, v[238:239], off
	v_lshl_add_u64 v[238:239], v[238:239], 0, s[46:47]
	global_load_dword v166, v[238:239], off
	v_lshl_add_u64 v[238:239], v[238:239], 0, s[46:47]
	global_load_dword v168, v[238:239], off
	v_lshl_add_u64 v[238:239], v[238:239], 0, s[46:47]
	global_load_dword v170, v[238:239], off
	v_lshl_add_u64 v[238:239], v[238:239], 0, s[46:47]
	global_load_dword v172, v[238:239], off
	v_lshl_add_u64 v[238:239], v[238:239], 0, s[46:47]
	global_load_dword v174, v[238:239], off
	v_lshl_add_u64 v[238:239], v[238:239], 0, s[46:47]
	global_load_dword v176, v[238:239], off
	v_lshl_add_u64 v[238:239], v[238:239], 0, s[46:47]
	global_load_dword v178, v[238:239], off
	v_lshl_add_u64 v[238:239], v[238:239], 0, s[46:47]
	global_load_dword v180, v[238:239], off
	v_lshl_add_u64 v[238:239], v[238:239], 0, s[46:47]
	global_load_dword v182, v[238:239], off
	v_lshl_add_u64 v[238:239], v[238:239], 0, s[46:47]
	global_load_dword v184, v[238:239], off
	v_lshl_add_u64 v[238:239], v[238:239], 0, s[46:47]
	global_load_dword v186, v[238:239], off
	v_lshl_add_u64 v[238:239], v[238:239], 0, s[46:47]
	global_load_dword v188, v[238:239], off
	v_lshl_add_u64 v[238:239], v[238:239], 0, s[46:47]
	global_load_dword v190, v[238:239], off
	v_lshl_add_u64 v[238:239], v[238:239], 0, s[46:47]
	global_load_dword v192, v[238:239], off
	v_lshl_add_u64 v[238:239], v[238:239], 0, s[46:47]
	global_load_dword v194, v[238:239], off
	v_lshl_add_u64 v[238:239], v[238:239], 0, s[46:47]
	global_load_dword v196, v[238:239], off
	v_lshl_add_u64 v[238:239], v[238:239], 0, s[46:47]
	global_load_dword v198, v[238:239], off
	v_lshl_add_u64 v[238:239], v[238:239], 0, s[46:47]
	global_load_dword v200, v[238:239], off
	v_lshl_add_u64 v[238:239], v[238:239], 0, s[46:47]
	global_load_dword v202, v[238:239], off
	v_lshl_add_u64 v[238:239], v[238:239], 0, s[46:47]
	global_load_dword v204, v[238:239], off
	v_lshl_add_u64 v[238:239], v[238:239], 0, s[46:47]
	global_load_dword v206, v[238:239], off
	v_lshl_add_u64 v[238:239], v[238:239], 0, s[46:47]
	global_load_dword v208, v[238:239], off
	v_lshl_add_u64 v[238:239], v[238:239], 0, s[46:47]
	global_load_dword v210, v[238:239], off
	v_lshl_add_u64 v[238:239], v[238:239], 0, s[46:47]
	global_load_dword v212, v[238:239], off
	v_lshl_add_u64 v[238:239], v[238:239], 0, s[46:47]
	global_load_dword v214, v[238:239], off
	v_lshl_add_u64 v[238:239], v[238:239], 0, s[46:47]
	global_load_dword v216, v[238:239], off
	v_lshl_add_u64 v[238:239], v[238:239], 0, s[46:47]
	global_load_dword v218, v[238:239], off
	v_lshl_add_u64 v[238:239], v[238:239], 0, s[46:47]
	global_load_dword v220, v[238:239], off
	v_lshl_add_u64 v[238:239], v[238:239], 0, s[46:47]
	global_load_dword v222, v[238:239], off
	v_lshl_add_u64 v[238:239], v[238:239], 0, s[46:47]
	global_load_dword v224, v[238:239], off
	v_lshl_add_u64 v[238:239], v[238:239], 0, s[46:47]
	global_load_dword v226, v[238:239], off
	v_lshl_add_u64 v[238:239], v[238:239], 0, s[46:47]
	global_load_dword v228, v[238:239], off
	v_lshl_add_u64 v[238:239], v[238:239], 0, s[46:47]
	global_load_dword v230, v[238:239], off
	v_lshl_add_u64 v[238:239], v[238:239], 0, s[46:47]
	global_load_dword v232, v[238:239], off
	v_lshl_add_u64 v[238:239], v[238:239], 0, s[46:47]
	ds_read_b128 v[22:25], v5 offset:4096
	ds_read_b128 v[26:29], v5 offset:8192
	ds_read_b128 v[30:33], v5 offset:12288
	ds_read_b128 v[34:37], v5 offset:16384
	ds_read_b128 v[38:41], v5 offset:20480
	ds_read_b128 v[42:45], v5 offset:24576
	ds_read_b128 v[46:49], v5 offset:28672
	ds_read_b128 v[50:53], v5
	ds_read_b128 v[54:57], v5 offset:32768
	s_waitcnt lgkmcnt(8)
; DI void mod_item(const KP& P, int l, int nc, LAS float* S  , LAS float* red  ) {
;     ...
;         const float* w = P.w_mod + (size_t)l * D * 6144 + n0 + col;
; #pragma unroll 4
;         for (int k = kq * 128; k < kq * 128 + 128; ++k) { const float wv = w[(size_t)k * 6144];
; #pragma unroll
;             for (int r = 0; r < 9; ++r) a[r] += S[r * D + k] * wv; }
	v_mov_b32_e32 v67, v22
	v_add_u32_e32 v5, 16, v5
	s_waitcnt lgkmcnt(1)
	v_mov_b32_e32 v66, v50
	v_mov_b32_e32 v22, v51
	v_mov_b32_e32 v50, v52
	v_mov_b32_e32 v51, v24
	v_mov_b32_e32 v24, v53
	v_mov_b32_e32 v52, v26
	v_mov_b32_e32 v53, v30
	v_mov_b32_e32 v30, v27
	v_mov_b32_e32 v26, v28
	v_mov_b32_e32 v27, v32
	v_mov_b32_e32 v32, v29
	v_mov_b32_e32 v28, v34
	v_mov_b32_e32 v29, v38
	v_mov_b32_e32 v38, v35
	v_mov_b32_e32 v34, v36
	v_mov_b32_e32 v35, v40
	v_mov_b32_e32 v40, v37
	v_mov_b32_e32 v36, v42
	v_mov_b32_e32 v37, v46
	v_mov_b32_e32 v46, v43
	v_mov_b32_e32 v42, v44
	v_mov_b32_e32 v43, v48
	v_mov_b32_e32 v48, v45
	s_waitcnt vmcnt(59)
	v_pk_fma_f32 v[10:11], v[108:109], v[66:67], v[10:11] op_sel_hi:[0,1,1]
	v_pk_fma_f32 v[12:13], v[108:109], v[52:53], v[12:13] op_sel_hi:[0,1,1]
	v_pk_fma_f32 v[16:17], v[108:109], v[28:29], v[16:17] op_sel_hi:[0,1,1]
	v_pk_fma_f32 v[14:15], v[108:109], v[36:37], v[14:15] op_sel_hi:[0,1,1]
	s_waitcnt lgkmcnt(0)
	v_fmac_f32_e32 v20, v108, v54
	s_waitcnt vmcnt(58)
	v_pk_fma_f32 v[10:11], v[110:111], v[22:23], v[10:11] op_sel_hi:[0,1,1]
	v_pk_fma_f32 v[12:13], v[110:111], v[30:31], v[12:13] op_sel_hi:[0,1,1]
	v_pk_fma_f32 v[16:17], v[110:111], v[38:39], v[16:17] op_sel_hi:[0,1,1]
	v_pk_fma_f32 v[14:15], v[110:111], v[46:47], v[14:15] op_sel_hi:[0,1,1]
	v_fmac_f32_e32 v20, v110, v55
	s_waitcnt vmcnt(57)
	v_pk_fma_f32 v[10:11], v[112:113], v[50:51], v[10:11] op_sel_hi:[0,1,1]
	v_pk_fma_f32 v[12:13], v[112:113], v[26:27], v[12:13] op_sel_hi:[0,1,1]
	v_pk_fma_f32 v[16:17], v[112:113], v[34:35], v[16:17] op_sel_hi:[0,1,1]
	v_pk_fma_f32 v[14:15], v[112:113], v[42:43], v[14:15] op_sel_hi:[0,1,1]
	v_fmac_f32_e32 v20, v112, v56
	s_waitcnt vmcnt(56)
	v_pk_fma_f32 v[10:11], v[114:115], v[24:25], v[10:11] op_sel_hi:[0,1,1]
	v_pk_fma_f32 v[12:13], v[114:115], v[32:33], v[12:13] op_sel_hi:[0,1,1]
	v_pk_fma_f32 v[16:17], v[114:115], v[40:41], v[16:17] op_sel_hi:[0,1,1]
	v_pk_fma_f32 v[14:15], v[114:115], v[48:49], v[14:15] op_sel_hi:[0,1,1]
	v_fmac_f32_e32 v20, v114, v57
	global_load_dword v108, v[238:239], off
	v_lshl_add_u64 v[238:239], v[238:239], 0, s[46:47]
	global_load_dword v110, v[238:239], off
	v_lshl_add_u64 v[238:239], v[238:239], 0, s[46:47]
	global_load_dword v112, v[238:239], off
	v_lshl_add_u64 v[238:239], v[238:239], 0, s[46:47]
	global_load_dword v114, v[238:239], off
	v_lshl_add_u64 v[238:239], v[238:239], 0, s[46:47]
	ds_read_b128 v[22:25], v5 offset:4096
	ds_read_b128 v[26:29], v5 offset:8192
	ds_read_b128 v[30:33], v5 offset:12288
	ds_read_b128 v[34:37], v5 offset:16384
	ds_read_b128 v[38:41], v5 offset:20480
	ds_read_b128 v[42:45], v5 offset:24576
	ds_read_b128 v[46:49], v5 offset:28672
	ds_read_b128 v[50:53], v5
	ds_read_b128 v[54:57], v5 offset:32768
	s_waitcnt lgkmcnt(8)
	v_mov_b32_e32 v67, v22
	v_add_u32_e32 v5, 16, v5
	s_waitcnt lgkmcnt(1)
	v_mov_b32_e32 v66, v50
	v_mov_b32_e32 v22, v51
	v_mov_b32_e32 v50, v52
	v_mov_b32_e32 v51, v24
	v_mov_b32_e32 v24, v53
	v_mov_b32_e32 v52, v26
	v_mov_b32_e32 v53, v30
	v_mov_b32_e32 v30, v27
	v_mov_b32_e32 v26, v28
	v_mov_b32_e32 v27, v32
	v_mov_b32_e32 v32, v29
	v_mov_b32_e32 v28, v34
	v_mov_b32_e32 v29, v38
	v_mov_b32_e32 v38, v35
	v_mov_b32_e32 v34, v36
	v_mov_b32_e32 v35, v40
	v_mov_b32_e32 v40, v37
	v_mov_b32_e32 v36, v42
	v_mov_b32_e32 v37, v46
	v_mov_b32_e32 v46, v43
	v_mov_b32_e32 v42, v44
	v_mov_b32_e32 v43, v48
	v_mov_b32_e32 v48, v45
	s_waitcnt vmcnt(59)
	v_pk_fma_f32 v[10:11], v[116:117], v[66:67], v[10:11] op_sel_hi:[0,1,1]
	v_pk_fma_f32 v[12:13], v[116:117], v[52:53], v[12:13] op_sel_hi:[0,1,1]
	v_pk_fma_f32 v[16:17], v[116:117], v[28:29], v[16:17] op_sel_hi:[0,1,1]
	v_pk_fma_f32 v[14:15], v[116:117], v[36:37], v[14:15] op_sel_hi:[0,1,1]
	s_waitcnt lgkmcnt(0)
	v_fmac_f32_e32 v20, v116, v54
	s_waitcnt vmcnt(58)
	v_pk_fma_f32 v[10:11], v[118:119], v[22:23], v[10:11] op_sel_hi:[0,1,1]
	v_pk_fma_f32 v[12:13], v[118:119], v[30:31], v[12:13] op_sel_hi:[0,1,1]
	v_pk_fma_f32 v[16:17], v[118:119], v[38:39], v[16:17] op_sel_hi:[0,1,1]
	v_pk_fma_f32 v[14:15], v[118:119], v[46:47], v[14:15] op_sel_hi:[0,1,1]
	v_fmac_f32_e32 v20, v118, v55
	s_waitcnt vmcnt(57)
	v_pk_fma_f32 v[10:11], v[120:121], v[50:51], v[10:11] op_sel_hi:[0,1,1]
	v_pk_fma_f32 v[12:13], v[120:121], v[26:27], v[12:13] op_sel_hi:[0,1,1]
	v_pk_fma_f32 v[16:17], v[120:121], v[34:35], v[16:17] op_sel_hi:[0,1,1]
	v_pk_fma_f32 v[14:15], v[120:121], v[42:43], v[14:15] op_sel_hi:[0,1,1]
	v_fmac_f32_e32 v20, v120, v56
	s_waitcnt vmcnt(56)
	v_pk_fma_f32 v[10:11], v[122:123], v[24:25], v[10:11] op_sel_hi:[0,1,1]
	v_pk_fma_f32 v[12:13], v[122:123], v[32:33], v[12:13] op_sel_hi:[0,1,1]
	v_pk_fma_f32 v[16:17], v[122:123], v[40:41], v[16:17] op_sel_hi:[0,1,1]
	v_pk_fma_f32 v[14:15], v[122:123], v[48:49], v[14:15] op_sel_hi:[0,1,1]
	v_fmac_f32_e32 v20, v122, v57
	global_load_dword v116, v[238:239], off
	v_lshl_add_u64 v[238:239], v[238:239], 0, s[46:47]
	global_load_dword v118, v[238:239], off
	v_lshl_add_u64 v[238:239], v[238:239], 0, s[46:47]
	global_load_dword v120, v[238:239], off
	v_lshl_add_u64 v[238:239], v[238:239], 0, s[46:47]
	global_load_dword v122, v[238:239], off
	v_lshl_add_u64 v[238:239], v[238:239], 0, s[46:47]
	ds_read_b128 v[22:25], v5 offset:4096
	ds_read_b128 v[26:29], v5 offset:8192
	ds_read_b128 v[30:33], v5 offset:12288
	ds_read_b128 v[34:37], v5 offset:16384
	ds_read_b128 v[38:41], v5 offset:20480
	ds_read_b128 v[42:45], v5 offset:24576
	ds_read_b128 v[46:49], v5 offset:28672
	ds_read_b128 v[50:53], v5
	ds_read_b128 v[54:57], v5 offset:32768
	s_waitcnt lgkmcnt(8)
	v_mov_b32_e32 v67, v22
	v_add_u32_e32 v5, 16, v5
	s_waitcnt lgkmcnt(1)
; DI void mod_item(const KP& P, int l, int nc, LAS float* S  , LAS float* red  ) {
;     ...
;         const float* w = P.w_mod + (size_t)l * D * 6144 + n0 + col;
; #pragma unroll 4
;         for (int k = kq * 128; k < kq * 128 + 128; ++k) { const float wv = w[(size_t)k * 6144];
; #pragma unroll
;             for (int r = 0; r < 9; ++r) a[r] += S[r * D + k] * wv; }
	v_mov_b32_e32 v66, v50
	v_mov_b32_e32 v22, v51
	v_mov_b32_e32 v50, v52
	v_mov_b32_e32 v51, v24
	v_mov_b32_e32 v24, v53
	v_mov_b32_e32 v52, v26
	v_mov_b32_e32 v53, v30
	v_mov_b32_e32 v30, v27
	v_mov_b32_e32 v26, v28
	v_mov_b32_e32 v27, v32
	v_mov_b32_e32 v32, v29
	v_mov_b32_e32 v28, v34
	v_mov_b32_e32 v29, v38
	v_mov_b32_e32 v38, v35
	v_mov_b32_e32 v34, v36
	v_mov_b32_e32 v35, v40
	v_mov_b32_e32 v40, v37
	v_mov_b32_e32 v36, v42
	v_mov_b32_e32 v37, v46
	v_mov_b32_e32 v46, v43
	v_mov_b32_e32 v42, v44
	v_mov_b32_e32 v43, v48
	v_mov_b32_e32 v48, v45
	s_waitcnt vmcnt(59)
	v_pk_fma_f32 v[10:11], v[124:125], v[66:67], v[10:11] op_sel_hi:[0,1,1]
	v_pk_fma_f32 v[12:13], v[124:125], v[52:53], v[12:13] op_sel_hi:[0,1,1]
	v_pk_fma_f32 v[16:17], v[124:125], v[28:29], v[16:17] op_sel_hi:[0,1,1]
	v_pk_fma_f32 v[14:15], v[124:125], v[36:37], v[14:15] op_sel_hi:[0,1,1]
	s_waitcnt lgkmcnt(0)
	v_fmac_f32_e32 v20, v124, v54
	s_waitcnt vmcnt(58)
	v_pk_fma_f32 v[10:11], v[126:127], v[22:23], v[10:11] op_sel_hi:[0,1,1]
	v_pk_fma_f32 v[12:13], v[126:127], v[30:31], v[12:13] op_sel_hi:[0,1,1]
	v_pk_fma_f32 v[16:17], v[126:127], v[38:39], v[16:17] op_sel_hi:[0,1,1]
	v_pk_fma_f32 v[14:15], v[126:127], v[46:47], v[14:15] op_sel_hi:[0,1,1]
	v_fmac_f32_e32 v20, v126, v55
	s_waitcnt vmcnt(57)
	v_pk_fma_f32 v[10:11], v[128:129], v[50:51], v[10:11] op_sel_hi:[0,1,1]
	v_pk_fma_f32 v[12:13], v[128:129], v[26:27], v[12:13] op_sel_hi:[0,1,1]
	v_pk_fma_f32 v[16:17], v[128:129], v[34:35], v[16:17] op_sel_hi:[0,1,1]
	v_pk_fma_f32 v[14:15], v[128:129], v[42:43], v[14:15] op_sel_hi:[0,1,1]
	v_fmac_f32_e32 v20, v128, v56
	s_waitcnt vmcnt(56)
	v_pk_fma_f32 v[10:11], v[130:131], v[24:25], v[10:11] op_sel_hi:[0,1,1]
	v_pk_fma_f32 v[12:13], v[130:131], v[32:33], v[12:13] op_sel_hi:[0,1,1]
	v_pk_fma_f32 v[16:17], v[130:131], v[40:41], v[16:17] op_sel_hi:[0,1,1]
	v_pk_fma_f32 v[14:15], v[130:131], v[48:49], v[14:15] op_sel_hi:[0,1,1]
	v_fmac_f32_e32 v20, v130, v57
	global_load_dword v124, v[238:239], off
	v_lshl_add_u64 v[238:239], v[238:239], 0, s[46:47]
	global_load_dword v126, v[238:239], off
	v_lshl_add_u64 v[238:239], v[238:239], 0, s[46:47]
	global_load_dword v128, v[238:239], off
	v_lshl_add_u64 v[238:239], v[238:239], 0, s[46:47]
	global_load_dword v130, v[238:239], off
	v_lshl_add_u64 v[238:239], v[238:239], 0, s[46:47]
	ds_read_b128 v[22:25], v5 offset:4096
	ds_read_b128 v[26:29], v5 offset:8192
	ds_read_b128 v[30:33], v5 offset:12288
	ds_read_b128 v[34:37], v5 offset:16384
	ds_read_b128 v[38:41], v5 offset:20480
	ds_read_b128 v[42:45], v5 offset:24576
	ds_read_b128 v[46:49], v5 offset:28672
	ds_read_b128 v[50:53], v5
	ds_read_b128 v[54:57], v5 offset:32768
	s_waitcnt lgkmcnt(8)
	v_mov_b32_e32 v67, v22
	v_add_u32_e32 v5, 16, v5
	s_waitcnt lgkmcnt(1)
	v_mov_b32_e32 v66, v50
	v_mov_b32_e32 v22, v51
	v_mov_b32_e32 v50, v52
	v_mov_b32_e32 v51, v24
	v_mov_b32_e32 v24, v53
	v_mov_b32_e32 v52, v26
	v_mov_b32_e32 v53, v30
	v_mov_b32_e32 v30, v27
	v_mov_b32_e32 v26, v28
	v_mov_b32_e32 v27, v32
	v_mov_b32_e32 v32, v29
	v_mov_b32_e32 v28, v34
	v_mov_b32_e32 v29, v38
	v_mov_b32_e32 v38, v35
	v_mov_b32_e32 v34, v36
	v_mov_b32_e32 v35, v40
	v_mov_b32_e32 v40, v37
	v_mov_b32_e32 v36, v42
	v_mov_b32_e32 v37, v46
	v_mov_b32_e32 v46, v43
	v_mov_b32_e32 v42, v44
	v_mov_b32_e32 v43, v48
	v_mov_b32_e32 v48, v45
	s_waitcnt vmcnt(59)
	v_pk_fma_f32 v[10:11], v[132:133], v[66:67], v[10:11] op_sel_hi:[0,1,1]
	v_pk_fma_f32 v[12:13], v[132:133], v[52:53], v[12:13] op_sel_hi:[0,1,1]
	v_pk_fma_f32 v[16:17], v[132:133], v[28:29], v[16:17] op_sel_hi:[0,1,1]
	v_pk_fma_f32 v[14:15], v[132:133], v[36:37], v[14:15] op_sel_hi:[0,1,1]
	s_waitcnt lgkmcnt(0)
	v_fmac_f32_e32 v20, v132, v54
	s_waitcnt vmcnt(58)
	v_pk_fma_f32 v[10:11], v[134:135], v[22:23], v[10:11] op_sel_hi:[0,1,1]
	v_pk_fma_f32 v[12:13], v[134:135], v[30:31], v[12:13] op_sel_hi:[0,1,1]
	v_pk_fma_f32 v[16:17], v[134:135], v[38:39], v[16:17] op_sel_hi:[0,1,1]
	v_pk_fma_f32 v[14:15], v[134:135], v[46:47], v[14:15] op_sel_hi:[0,1,1]
	v_fmac_f32_e32 v20, v134, v55
	s_waitcnt vmcnt(57)
	v_pk_fma_f32 v[10:11], v[136:137], v[50:51], v[10:11] op_sel_hi:[0,1,1]
	v_pk_fma_f32 v[12:13], v[136:137], v[26:27], v[12:13] op_sel_hi:[0,1,1]
	v_pk_fma_f32 v[16:17], v[136:137], v[34:35], v[16:17] op_sel_hi:[0,1,1]
	v_pk_fma_f32 v[14:15], v[136:137], v[42:43], v[14:15] op_sel_hi:[0,1,1]
	v_fmac_f32_e32 v20, v136, v56
	s_waitcnt vmcnt(56)
	v_pk_fma_f32 v[10:11], v[138:139], v[24:25], v[10:11] op_sel_hi:[0,1,1]
	v_pk_fma_f32 v[12:13], v[138:139], v[32:33], v[12:13] op_sel_hi:[0,1,1]
	v_pk_fma_f32 v[16:17], v[138:139], v[40:41], v[16:17] op_sel_hi:[0,1,1]
	v_pk_fma_f32 v[14:15], v[138:139], v[48:49], v[14:15] op_sel_hi:[0,1,1]
	v_fmac_f32_e32 v20, v138, v57
	global_load_dword v132, v[238:239], off
	v_lshl_add_u64 v[238:239], v[238:239], 0, s[46:47]
	global_load_dword v134, v[238:239], off
	v_lshl_add_u64 v[238:239], v[238:239], 0, s[46:47]
	global_load_dword v136, v[238:239], off
	v_lshl_add_u64 v[238:239], v[238:239], 0, s[46:47]
	global_load_dword v138, v[238:239], off
	v_lshl_add_u64 v[238:239], v[238:239], 0, s[46:47]
	ds_read_b128 v[22:25], v5 offset:4096
	ds_read_b128 v[26:29], v5 offset:8192
	ds_read_b128 v[30:33], v5 offset:12288
	ds_read_b128 v[34:37], v5 offset:16384
	ds_read_b128 v[38:41], v5 offset:20480
	ds_read_b128 v[42:45], v5 offset:24576
	ds_read_b128 v[46:49], v5 offset:28672
	ds_read_b128 v[50:53], v5
	ds_read_b128 v[54:57], v5 offset:32768
	s_waitcnt lgkmcnt(8)
	v_mov_b32_e32 v67, v22
	v_add_u32_e32 v5, 16, v5
	s_waitcnt lgkmcnt(1)
; DI void mod_item(const KP& P, int l, int nc, LAS float* S  , LAS float* red  ) {
;     ...
;         const float* w = P.w_mod + (size_t)l * D * 6144 + n0 + col;
; #pragma unroll 4
;         for (int k = kq * 128; k < kq * 128 + 128; ++k) { const float wv = w[(size_t)k * 6144];
; #pragma unroll
;             for (int r = 0; r < 9; ++r) a[r] += S[r * D + k] * wv; }
	v_mov_b32_e32 v66, v50
	v_mov_b32_e32 v22, v51
	v_mov_b32_e32 v50, v52
	v_mov_b32_e32 v51, v24
	v_mov_b32_e32 v24, v53
	v_mov_b32_e32 v52, v26
	v_mov_b32_e32 v53, v30
	v_mov_b32_e32 v30, v27
	v_mov_b32_e32 v26, v28
	v_mov_b32_e32 v27, v32
	v_mov_b32_e32 v32, v29
	v_mov_b32_e32 v28, v34
	v_mov_b32_e32 v29, v38
	v_mov_b32_e32 v38, v35
	v_mov_b32_e32 v34, v36
	v_mov_b32_e32 v35, v40
	v_mov_b32_e32 v40, v37
	v_mov_b32_e32 v36, v42
	v_mov_b32_e32 v37, v46
	v_mov_b32_e32 v46, v43
	v_mov_b32_e32 v42, v44
	v_mov_b32_e32 v43, v48
	v_mov_b32_e32 v48, v45
	s_waitcnt vmcnt(59)
	v_pk_fma_f32 v[10:11], v[146:147], v[66:67], v[10:11] op_sel_hi:[0,1,1]
	v_pk_fma_f32 v[12:13], v[146:147], v[52:53], v[12:13] op_sel_hi:[0,1,1]
	v_pk_fma_f32 v[16:17], v[146:147], v[28:29], v[16:17] op_sel_hi:[0,1,1]
	v_pk_fma_f32 v[14:15], v[146:147], v[36:37], v[14:15] op_sel_hi:[0,1,1]
	s_waitcnt lgkmcnt(0)
	v_fmac_f32_e32 v20, v146, v54
	s_waitcnt vmcnt(58)
	v_pk_fma_f32 v[10:11], v[148:149], v[22:23], v[10:11] op_sel_hi:[0,1,1]
	v_pk_fma_f32 v[12:13], v[148:149], v[30:31], v[12:13] op_sel_hi:[0,1,1]
	v_pk_fma_f32 v[16:17], v[148:149], v[38:39], v[16:17] op_sel_hi:[0,1,1]
	v_pk_fma_f32 v[14:15], v[148:149], v[46:47], v[14:15] op_sel_hi:[0,1,1]
	v_fmac_f32_e32 v20, v148, v55
	s_waitcnt vmcnt(57)
	v_pk_fma_f32 v[10:11], v[150:151], v[50:51], v[10:11] op_sel_hi:[0,1,1]
	v_pk_fma_f32 v[12:13], v[150:151], v[26:27], v[12:13] op_sel_hi:[0,1,1]
	v_pk_fma_f32 v[16:17], v[150:151], v[34:35], v[16:17] op_sel_hi:[0,1,1]
	v_pk_fma_f32 v[14:15], v[150:151], v[42:43], v[14:15] op_sel_hi:[0,1,1]
	v_fmac_f32_e32 v20, v150, v56
	s_waitcnt vmcnt(56)
	v_pk_fma_f32 v[10:11], v[152:153], v[24:25], v[10:11] op_sel_hi:[0,1,1]
	v_pk_fma_f32 v[12:13], v[152:153], v[32:33], v[12:13] op_sel_hi:[0,1,1]
	v_pk_fma_f32 v[16:17], v[152:153], v[40:41], v[16:17] op_sel_hi:[0,1,1]
	v_pk_fma_f32 v[14:15], v[152:153], v[48:49], v[14:15] op_sel_hi:[0,1,1]
	v_fmac_f32_e32 v20, v152, v57
	global_load_dword v146, v[238:239], off
	v_lshl_add_u64 v[238:239], v[238:239], 0, s[46:47]
	global_load_dword v148, v[238:239], off
	v_lshl_add_u64 v[238:239], v[238:239], 0, s[46:47]
	global_load_dword v150, v[238:239], off
	v_lshl_add_u64 v[238:239], v[238:239], 0, s[46:47]
	global_load_dword v152, v[238:239], off
	v_lshl_add_u64 v[238:239], v[238:239], 0, s[46:47]
	ds_read_b128 v[22:25], v5 offset:4096
	ds_read_b128 v[26:29], v5 offset:8192
	ds_read_b128 v[30:33], v5 offset:12288
	ds_read_b128 v[34:37], v5 offset:16384
	ds_read_b128 v[38:41], v5 offset:20480
	ds_read_b128 v[42:45], v5 offset:24576
	ds_read_b128 v[46:49], v5 offset:28672
	ds_read_b128 v[50:53], v5
	ds_read_b128 v[54:57], v5 offset:32768
	s_waitcnt lgkmcnt(8)
	v_mov_b32_e32 v67, v22
	v_add_u32_e32 v5, 16, v5
	s_waitcnt lgkmcnt(1)
	v_mov_b32_e32 v66, v50
	v_mov_b32_e32 v22, v51
	v_mov_b32_e32 v50, v52
	v_mov_b32_e32 v51, v24
	v_mov_b32_e32 v24, v53
	v_mov_b32_e32 v52, v26
	v_mov_b32_e32 v53, v30
	v_mov_b32_e32 v30, v27
	v_mov_b32_e32 v26, v28
	v_mov_b32_e32 v27, v32
	v_mov_b32_e32 v32, v29
	v_mov_b32_e32 v28, v34
	v_mov_b32_e32 v29, v38
	v_mov_b32_e32 v38, v35
	v_mov_b32_e32 v34, v36
	v_mov_b32_e32 v35, v40
	v_mov_b32_e32 v40, v37
	v_mov_b32_e32 v36, v42
	v_mov_b32_e32 v37, v46
	v_mov_b32_e32 v46, v43
	v_mov_b32_e32 v42, v44
	v_mov_b32_e32 v43, v48
	v_mov_b32_e32 v48, v45
	s_waitcnt vmcnt(59)
	v_pk_fma_f32 v[10:11], v[154:155], v[66:67], v[10:11] op_sel_hi:[0,1,1]
	v_pk_fma_f32 v[12:13], v[154:155], v[52:53], v[12:13] op_sel_hi:[0,1,1]
	v_pk_fma_f32 v[16:17], v[154:155], v[28:29], v[16:17] op_sel_hi:[0,1,1]
	v_pk_fma_f32 v[14:15], v[154:155], v[36:37], v[14:15] op_sel_hi:[0,1,1]
	s_waitcnt lgkmcnt(0)
	v_fmac_f32_e32 v20, v154, v54
	s_waitcnt vmcnt(58)
	v_pk_fma_f32 v[10:11], v[156:157], v[22:23], v[10:11] op_sel_hi:[0,1,1]
	v_pk_fma_f32 v[12:13], v[156:157], v[30:31], v[12:13] op_sel_hi:[0,1,1]
	v_pk_fma_f32 v[16:17], v[156:157], v[38:39], v[16:17] op_sel_hi:[0,1,1]
	v_pk_fma_f32 v[14:15], v[156:157], v[46:47], v[14:15] op_sel_hi:[0,1,1]
	v_fmac_f32_e32 v20, v156, v55
	s_waitcnt vmcnt(57)
	v_pk_fma_f32 v[10:11], v[158:159], v[50:51], v[10:11] op_sel_hi:[0,1,1]
	v_pk_fma_f32 v[12:13], v[158:159], v[26:27], v[12:13] op_sel_hi:[0,1,1]
	v_pk_fma_f32 v[16:17], v[158:159], v[34:35], v[16:17] op_sel_hi:[0,1,1]
	v_pk_fma_f32 v[14:15], v[158:159], v[42:43], v[14:15] op_sel_hi:[0,1,1]
	v_fmac_f32_e32 v20, v158, v56
	s_waitcnt vmcnt(56)
	v_pk_fma_f32 v[10:11], v[160:161], v[24:25], v[10:11] op_sel_hi:[0,1,1]
	v_pk_fma_f32 v[12:13], v[160:161], v[32:33], v[12:13] op_sel_hi:[0,1,1]
	v_pk_fma_f32 v[16:17], v[160:161], v[40:41], v[16:17] op_sel_hi:[0,1,1]
	v_pk_fma_f32 v[14:15], v[160:161], v[48:49], v[14:15] op_sel_hi:[0,1,1]
	v_fmac_f32_e32 v20, v160, v57
	global_load_dword v154, v[238:239], off
	v_lshl_add_u64 v[238:239], v[238:239], 0, s[46:47]
	global_load_dword v156, v[238:239], off
	v_lshl_add_u64 v[238:239], v[238:239], 0, s[46:47]
	global_load_dword v158, v[238:239], off
	v_lshl_add_u64 v[238:239], v[238:239], 0, s[46:47]
	global_load_dword v160, v[238:239], off
	v_lshl_add_u64 v[238:239], v[238:239], 0, s[46:47]
	ds_read_b128 v[22:25], v5 offset:4096
	ds_read_b128 v[26:29], v5 offset:8192
	ds_read_b128 v[30:33], v5 offset:12288
	ds_read_b128 v[34:37], v5 offset:16384
	ds_read_b128 v[38:41], v5 offset:20480
	ds_read_b128 v[42:45], v5 offset:24576
	ds_read_b128 v[46:49], v5 offset:28672
	ds_read_b128 v[50:53], v5
	ds_read_b128 v[54:57], v5 offset:32768
	s_waitcnt lgkmcnt(8)
	v_mov_b32_e32 v67, v22
	v_add_u32_e32 v5, 16, v5
	s_waitcnt lgkmcnt(1)
; DI void mod_item(const KP& P, int l, int nc, LAS float* S  , LAS float* red  ) {
;     ...
;         const float* w = P.w_mod + (size_t)l * D * 6144 + n0 + col;
; #pragma unroll 4
;         for (int k = kq * 128; k < kq * 128 + 128; ++k) { const float wv = w[(size_t)k * 6144];
; #pragma unroll
;             for (int r = 0; r < 9; ++r) a[r] += S[r * D + k] * wv; }
	v_mov_b32_e32 v66, v50
	v_mov_b32_e32 v22, v51
	v_mov_b32_e32 v50, v52
	v_mov_b32_e32 v51, v24
	v_mov_b32_e32 v24, v53
	v_mov_b32_e32 v52, v26
	v_mov_b32_e32 v53, v30
	v_mov_b32_e32 v30, v27
	v_mov_b32_e32 v26, v28
	v_mov_b32_e32 v27, v32
	v_mov_b32_e32 v32, v29
	v_mov_b32_e32 v28, v34
	v_mov_b32_e32 v29, v38
	v_mov_b32_e32 v38, v35
	v_mov_b32_e32 v34, v36
	v_mov_b32_e32 v35, v40
	v_mov_b32_e32 v40, v37
	v_mov_b32_e32 v36, v42
	v_mov_b32_e32 v37, v46
	v_mov_b32_e32 v46, v43
	v_mov_b32_e32 v42, v44
	v_mov_b32_e32 v43, v48
	v_mov_b32_e32 v48, v45
	s_waitcnt vmcnt(59)
	v_pk_fma_f32 v[10:11], v[162:163], v[66:67], v[10:11] op_sel_hi:[0,1,1]
	v_pk_fma_f32 v[12:13], v[162:163], v[52:53], v[12:13] op_sel_hi:[0,1,1]
	v_pk_fma_f32 v[16:17], v[162:163], v[28:29], v[16:17] op_sel_hi:[0,1,1]
	v_pk_fma_f32 v[14:15], v[162:163], v[36:37], v[14:15] op_sel_hi:[0,1,1]
	s_waitcnt lgkmcnt(0)
	v_fmac_f32_e32 v20, v162, v54
	s_waitcnt vmcnt(58)
	v_pk_fma_f32 v[10:11], v[164:165], v[22:23], v[10:11] op_sel_hi:[0,1,1]
	v_pk_fma_f32 v[12:13], v[164:165], v[30:31], v[12:13] op_sel_hi:[0,1,1]
	v_pk_fma_f32 v[16:17], v[164:165], v[38:39], v[16:17] op_sel_hi:[0,1,1]
	v_pk_fma_f32 v[14:15], v[164:165], v[46:47], v[14:15] op_sel_hi:[0,1,1]
	v_fmac_f32_e32 v20, v164, v55
	s_waitcnt vmcnt(57)
	v_pk_fma_f32 v[10:11], v[166:167], v[50:51], v[10:11] op_sel_hi:[0,1,1]
	v_pk_fma_f32 v[12:13], v[166:167], v[26:27], v[12:13] op_sel_hi:[0,1,1]
	v_pk_fma_f32 v[16:17], v[166:167], v[34:35], v[16:17] op_sel_hi:[0,1,1]
	v_pk_fma_f32 v[14:15], v[166:167], v[42:43], v[14:15] op_sel_hi:[0,1,1]
	v_fmac_f32_e32 v20, v166, v56
	s_waitcnt vmcnt(56)
	v_pk_fma_f32 v[10:11], v[168:169], v[24:25], v[10:11] op_sel_hi:[0,1,1]
	v_pk_fma_f32 v[12:13], v[168:169], v[32:33], v[12:13] op_sel_hi:[0,1,1]
	v_pk_fma_f32 v[16:17], v[168:169], v[40:41], v[16:17] op_sel_hi:[0,1,1]
	v_pk_fma_f32 v[14:15], v[168:169], v[48:49], v[14:15] op_sel_hi:[0,1,1]
	v_fmac_f32_e32 v20, v168, v57
	global_load_dword v162, v[238:239], off
	v_lshl_add_u64 v[238:239], v[238:239], 0, s[46:47]
	global_load_dword v164, v[238:239], off
	v_lshl_add_u64 v[238:239], v[238:239], 0, s[46:47]
	global_load_dword v166, v[238:239], off
	v_lshl_add_u64 v[238:239], v[238:239], 0, s[46:47]
	global_load_dword v168, v[238:239], off
	v_lshl_add_u64 v[238:239], v[238:239], 0, s[46:47]
	ds_read_b128 v[22:25], v5 offset:4096
	ds_read_b128 v[26:29], v5 offset:8192
	ds_read_b128 v[30:33], v5 offset:12288
	ds_read_b128 v[34:37], v5 offset:16384
	ds_read_b128 v[38:41], v5 offset:20480
	ds_read_b128 v[42:45], v5 offset:24576
	ds_read_b128 v[46:49], v5 offset:28672
	ds_read_b128 v[50:53], v5
	ds_read_b128 v[54:57], v5 offset:32768
	s_waitcnt lgkmcnt(8)
	v_mov_b32_e32 v67, v22
	v_add_u32_e32 v5, 16, v5
	s_waitcnt lgkmcnt(1)
	v_mov_b32_e32 v66, v50
	v_mov_b32_e32 v22, v51
	v_mov_b32_e32 v50, v52
	v_mov_b32_e32 v51, v24
	v_mov_b32_e32 v24, v53
	v_mov_b32_e32 v52, v26
	v_mov_b32_e32 v53, v30
	v_mov_b32_e32 v30, v27
	v_mov_b32_e32 v26, v28
	v_mov_b32_e32 v27, v32
	v_mov_b32_e32 v32, v29
	v_mov_b32_e32 v28, v34
	v_mov_b32_e32 v29, v38
	v_mov_b32_e32 v38, v35
	v_mov_b32_e32 v34, v36
	v_mov_b32_e32 v35, v40
	v_mov_b32_e32 v40, v37
	v_mov_b32_e32 v36, v42
	v_mov_b32_e32 v37, v46
	v_mov_b32_e32 v46, v43
	v_mov_b32_e32 v42, v44
	v_mov_b32_e32 v43, v48
	v_mov_b32_e32 v48, v45
	s_waitcnt vmcnt(59)
	v_pk_fma_f32 v[10:11], v[170:171], v[66:67], v[10:11] op_sel_hi:[0,1,1]
	v_pk_fma_f32 v[12:13], v[170:171], v[52:53], v[12:13] op_sel_hi:[0,1,1]
	v_pk_fma_f32 v[16:17], v[170:171], v[28:29], v[16:17] op_sel_hi:[0,1,1]
	v_pk_fma_f32 v[14:15], v[170:171], v[36:37], v[14:15] op_sel_hi:[0,1,1]
	s_waitcnt lgkmcnt(0)
	v_fmac_f32_e32 v20, v170, v54
	s_waitcnt vmcnt(58)
	v_pk_fma_f32 v[10:11], v[172:173], v[22:23], v[10:11] op_sel_hi:[0,1,1]
	v_pk_fma_f32 v[12:13], v[172:173], v[30:31], v[12:13] op_sel_hi:[0,1,1]
	v_pk_fma_f32 v[16:17], v[172:173], v[38:39], v[16:17] op_sel_hi:[0,1,1]
	v_pk_fma_f32 v[14:15], v[172:173], v[46:47], v[14:15] op_sel_hi:[0,1,1]
	v_fmac_f32_e32 v20, v172, v55
	s_waitcnt vmcnt(57)
	v_pk_fma_f32 v[10:11], v[174:175], v[50:51], v[10:11] op_sel_hi:[0,1,1]
	v_pk_fma_f32 v[12:13], v[174:175], v[26:27], v[12:13] op_sel_hi:[0,1,1]
	v_pk_fma_f32 v[16:17], v[174:175], v[34:35], v[16:17] op_sel_hi:[0,1,1]
	v_pk_fma_f32 v[14:15], v[174:175], v[42:43], v[14:15] op_sel_hi:[0,1,1]
	v_fmac_f32_e32 v20, v174, v56
	s_waitcnt vmcnt(56)
	v_pk_fma_f32 v[10:11], v[176:177], v[24:25], v[10:11] op_sel_hi:[0,1,1]
	v_pk_fma_f32 v[12:13], v[176:177], v[32:33], v[12:13] op_sel_hi:[0,1,1]
	v_pk_fma_f32 v[16:17], v[176:177], v[40:41], v[16:17] op_sel_hi:[0,1,1]
	v_pk_fma_f32 v[14:15], v[176:177], v[48:49], v[14:15] op_sel_hi:[0,1,1]
	v_fmac_f32_e32 v20, v176, v57
	global_load_dword v170, v[238:239], off
	v_lshl_add_u64 v[238:239], v[238:239], 0, s[46:47]
	global_load_dword v172, v[238:239], off
	v_lshl_add_u64 v[238:239], v[238:239], 0, s[46:47]
	global_load_dword v174, v[238:239], off
	v_lshl_add_u64 v[238:239], v[238:239], 0, s[46:47]
	global_load_dword v176, v[238:239], off
	v_lshl_add_u64 v[238:239], v[238:239], 0, s[46:47]
	ds_read_b128 v[22:25], v5 offset:4096
	ds_read_b128 v[26:29], v5 offset:8192
	ds_read_b128 v[30:33], v5 offset:12288
	ds_read_b128 v[34:37], v5 offset:16384
	ds_read_b128 v[38:41], v5 offset:20480
	ds_read_b128 v[42:45], v5 offset:24576
	ds_read_b128 v[46:49], v5 offset:28672
	ds_read_b128 v[50:53], v5
	ds_read_b128 v[54:57], v5 offset:32768
	s_waitcnt lgkmcnt(8)
	v_mov_b32_e32 v67, v22
	v_add_u32_e32 v5, 16, v5
	s_waitcnt lgkmcnt(1)
; DI void mod_item(const KP& P, int l, int nc, LAS float* S  , LAS float* red  ) {
;     ...
;         const float* w = P.w_mod + (size_t)l * D * 6144 + n0 + col;
; #pragma unroll 4
;         for (int k = kq * 128; k < kq * 128 + 128; ++k) { const float wv = w[(size_t)k * 6144];
; #pragma unroll
;             for (int r = 0; r < 9; ++r) a[r] += S[r * D + k] * wv; }
	v_mov_b32_e32 v66, v50
	v_mov_b32_e32 v22, v51
	v_mov_b32_e32 v50, v52
	v_mov_b32_e32 v51, v24
	v_mov_b32_e32 v24, v53
	v_mov_b32_e32 v52, v26
	v_mov_b32_e32 v53, v30
	v_mov_b32_e32 v30, v27
	v_mov_b32_e32 v26, v28
	v_mov_b32_e32 v27, v32
	v_mov_b32_e32 v32, v29
	v_mov_b32_e32 v28, v34
	v_mov_b32_e32 v29, v38
	v_mov_b32_e32 v38, v35
	v_mov_b32_e32 v34, v36
	v_mov_b32_e32 v35, v40
	v_mov_b32_e32 v40, v37
	v_mov_b32_e32 v36, v42
	v_mov_b32_e32 v37, v46
	v_mov_b32_e32 v46, v43
	v_mov_b32_e32 v42, v44
	v_mov_b32_e32 v43, v48
	v_mov_b32_e32 v48, v45
	s_waitcnt vmcnt(59)
	v_pk_fma_f32 v[10:11], v[178:179], v[66:67], v[10:11] op_sel_hi:[0,1,1]
	v_pk_fma_f32 v[12:13], v[178:179], v[52:53], v[12:13] op_sel_hi:[0,1,1]
	v_pk_fma_f32 v[16:17], v[178:179], v[28:29], v[16:17] op_sel_hi:[0,1,1]
	v_pk_fma_f32 v[14:15], v[178:179], v[36:37], v[14:15] op_sel_hi:[0,1,1]
	s_waitcnt lgkmcnt(0)
	v_fmac_f32_e32 v20, v178, v54
	s_waitcnt vmcnt(58)
	v_pk_fma_f32 v[10:11], v[180:181], v[22:23], v[10:11] op_sel_hi:[0,1,1]
	v_pk_fma_f32 v[12:13], v[180:181], v[30:31], v[12:13] op_sel_hi:[0,1,1]
	v_pk_fma_f32 v[16:17], v[180:181], v[38:39], v[16:17] op_sel_hi:[0,1,1]
	v_pk_fma_f32 v[14:15], v[180:181], v[46:47], v[14:15] op_sel_hi:[0,1,1]
	v_fmac_f32_e32 v20, v180, v55
	s_waitcnt vmcnt(57)
	v_pk_fma_f32 v[10:11], v[182:183], v[50:51], v[10:11] op_sel_hi:[0,1,1]
	v_pk_fma_f32 v[12:13], v[182:183], v[26:27], v[12:13] op_sel_hi:[0,1,1]
	v_pk_fma_f32 v[16:17], v[182:183], v[34:35], v[16:17] op_sel_hi:[0,1,1]
	v_pk_fma_f32 v[14:15], v[182:183], v[42:43], v[14:15] op_sel_hi:[0,1,1]
	v_fmac_f32_e32 v20, v182, v56
	s_waitcnt vmcnt(56)
	v_pk_fma_f32 v[10:11], v[184:185], v[24:25], v[10:11] op_sel_hi:[0,1,1]
	v_pk_fma_f32 v[12:13], v[184:185], v[32:33], v[12:13] op_sel_hi:[0,1,1]
	v_pk_fma_f32 v[16:17], v[184:185], v[40:41], v[16:17] op_sel_hi:[0,1,1]
	v_pk_fma_f32 v[14:15], v[184:185], v[48:49], v[14:15] op_sel_hi:[0,1,1]
	v_fmac_f32_e32 v20, v184, v57
	global_load_dword v178, v[238:239], off
	v_lshl_add_u64 v[238:239], v[238:239], 0, s[46:47]
	global_load_dword v180, v[238:239], off
	v_lshl_add_u64 v[238:239], v[238:239], 0, s[46:47]
	global_load_dword v182, v[238:239], off
	v_lshl_add_u64 v[238:239], v[238:239], 0, s[46:47]
	global_load_dword v184, v[238:239], off
	v_lshl_add_u64 v[238:239], v[238:239], 0, s[46:47]
	ds_read_b128 v[22:25], v5 offset:4096
	ds_read_b128 v[26:29], v5 offset:8192
	ds_read_b128 v[30:33], v5 offset:12288
	ds_read_b128 v[34:37], v5 offset:16384
	ds_read_b128 v[38:41], v5 offset:20480
	ds_read_b128 v[42:45], v5 offset:24576
	ds_read_b128 v[46:49], v5 offset:28672
	ds_read_b128 v[50:53], v5
	ds_read_b128 v[54:57], v5 offset:32768
	s_waitcnt lgkmcnt(8)
	v_mov_b32_e32 v67, v22
	v_add_u32_e32 v5, 16, v5
	s_waitcnt lgkmcnt(1)
	v_mov_b32_e32 v66, v50
	v_mov_b32_e32 v22, v51
	v_mov_b32_e32 v50, v52
	v_mov_b32_e32 v51, v24
	v_mov_b32_e32 v24, v53
	v_mov_b32_e32 v52, v26
	v_mov_b32_e32 v53, v30
	v_mov_b32_e32 v30, v27
	v_mov_b32_e32 v26, v28
	v_mov_b32_e32 v27, v32
	v_mov_b32_e32 v32, v29
	v_mov_b32_e32 v28, v34
	v_mov_b32_e32 v29, v38
	v_mov_b32_e32 v38, v35
	v_mov_b32_e32 v34, v36
	v_mov_b32_e32 v35, v40
	v_mov_b32_e32 v40, v37
	v_mov_b32_e32 v36, v42
	v_mov_b32_e32 v37, v46
	v_mov_b32_e32 v46, v43
	v_mov_b32_e32 v42, v44
	v_mov_b32_e32 v43, v48
	v_mov_b32_e32 v48, v45
	s_waitcnt vmcnt(59)
	v_pk_fma_f32 v[10:11], v[186:187], v[66:67], v[10:11] op_sel_hi:[0,1,1]
	v_pk_fma_f32 v[12:13], v[186:187], v[52:53], v[12:13] op_sel_hi:[0,1,1]
	v_pk_fma_f32 v[16:17], v[186:187], v[28:29], v[16:17] op_sel_hi:[0,1,1]
	v_pk_fma_f32 v[14:15], v[186:187], v[36:37], v[14:15] op_sel_hi:[0,1,1]
	s_waitcnt lgkmcnt(0)
	v_fmac_f32_e32 v20, v186, v54
	s_waitcnt vmcnt(58)
	v_pk_fma_f32 v[10:11], v[188:189], v[22:23], v[10:11] op_sel_hi:[0,1,1]
	v_pk_fma_f32 v[12:13], v[188:189], v[30:31], v[12:13] op_sel_hi:[0,1,1]
	v_pk_fma_f32 v[16:17], v[188:189], v[38:39], v[16:17] op_sel_hi:[0,1,1]
	v_pk_fma_f32 v[14:15], v[188:189], v[46:47], v[14:15] op_sel_hi:[0,1,1]
	v_fmac_f32_e32 v20, v188, v55
	s_waitcnt vmcnt(57)
	v_pk_fma_f32 v[10:11], v[190:191], v[50:51], v[10:11] op_sel_hi:[0,1,1]
	v_pk_fma_f32 v[12:13], v[190:191], v[26:27], v[12:13] op_sel_hi:[0,1,1]
	v_pk_fma_f32 v[16:17], v[190:191], v[34:35], v[16:17] op_sel_hi:[0,1,1]
	v_pk_fma_f32 v[14:15], v[190:191], v[42:43], v[14:15] op_sel_hi:[0,1,1]
	v_fmac_f32_e32 v20, v190, v56
	s_waitcnt vmcnt(56)
	v_pk_fma_f32 v[10:11], v[192:193], v[24:25], v[10:11] op_sel_hi:[0,1,1]
	v_pk_fma_f32 v[12:13], v[192:193], v[32:33], v[12:13] op_sel_hi:[0,1,1]
	v_pk_fma_f32 v[16:17], v[192:193], v[40:41], v[16:17] op_sel_hi:[0,1,1]
	v_pk_fma_f32 v[14:15], v[192:193], v[48:49], v[14:15] op_sel_hi:[0,1,1]
	v_fmac_f32_e32 v20, v192, v57
	global_load_dword v186, v[238:239], off
	v_lshl_add_u64 v[238:239], v[238:239], 0, s[46:47]
	global_load_dword v188, v[238:239], off
	v_lshl_add_u64 v[238:239], v[238:239], 0, s[46:47]
	global_load_dword v190, v[238:239], off
	v_lshl_add_u64 v[238:239], v[238:239], 0, s[46:47]
	global_load_dword v192, v[238:239], off
	v_lshl_add_u64 v[238:239], v[238:239], 0, s[46:47]
	ds_read_b128 v[22:25], v5 offset:4096
	ds_read_b128 v[26:29], v5 offset:8192
	ds_read_b128 v[30:33], v5 offset:12288
	ds_read_b128 v[34:37], v5 offset:16384
	ds_read_b128 v[38:41], v5 offset:20480
	ds_read_b128 v[42:45], v5 offset:24576
	ds_read_b128 v[46:49], v5 offset:28672
	ds_read_b128 v[50:53], v5
	ds_read_b128 v[54:57], v5 offset:32768
	s_waitcnt lgkmcnt(8)
	v_mov_b32_e32 v67, v22
	v_add_u32_e32 v5, 16, v5
	s_waitcnt lgkmcnt(1)
; DI void mod_item(const KP& P, int l, int nc, LAS float* S  , LAS float* red  ) {
;     ...
;         const float* w = P.w_mod + (size_t)l * D * 6144 + n0 + col;
; #pragma unroll 4
;         for (int k = kq * 128; k < kq * 128 + 128; ++k) { const float wv = w[(size_t)k * 6144];
; #pragma unroll
;             for (int r = 0; r < 9; ++r) a[r] += S[r * D + k] * wv; }
	v_mov_b32_e32 v66, v50
	v_mov_b32_e32 v22, v51
	v_mov_b32_e32 v50, v52
	v_mov_b32_e32 v51, v24
	v_mov_b32_e32 v24, v53
	v_mov_b32_e32 v52, v26
	v_mov_b32_e32 v53, v30
	v_mov_b32_e32 v30, v27
	v_mov_b32_e32 v26, v28
	v_mov_b32_e32 v27, v32
	v_mov_b32_e32 v32, v29
	v_mov_b32_e32 v28, v34
	v_mov_b32_e32 v29, v38
	v_mov_b32_e32 v38, v35
	v_mov_b32_e32 v34, v36
	v_mov_b32_e32 v35, v40
	v_mov_b32_e32 v40, v37
	v_mov_b32_e32 v36, v42
	v_mov_b32_e32 v37, v46
	v_mov_b32_e32 v46, v43
	v_mov_b32_e32 v42, v44
	v_mov_b32_e32 v43, v48
	v_mov_b32_e32 v48, v45
	s_waitcnt vmcnt(59)
	v_pk_fma_f32 v[10:11], v[194:195], v[66:67], v[10:11] op_sel_hi:[0,1,1]
	v_pk_fma_f32 v[12:13], v[194:195], v[52:53], v[12:13] op_sel_hi:[0,1,1]
	v_pk_fma_f32 v[16:17], v[194:195], v[28:29], v[16:17] op_sel_hi:[0,1,1]
	v_pk_fma_f32 v[14:15], v[194:195], v[36:37], v[14:15] op_sel_hi:[0,1,1]
	s_waitcnt lgkmcnt(0)
	v_fmac_f32_e32 v20, v194, v54
	s_waitcnt vmcnt(58)
	v_pk_fma_f32 v[10:11], v[196:197], v[22:23], v[10:11] op_sel_hi:[0,1,1]
	v_pk_fma_f32 v[12:13], v[196:197], v[30:31], v[12:13] op_sel_hi:[0,1,1]
	v_pk_fma_f32 v[16:17], v[196:197], v[38:39], v[16:17] op_sel_hi:[0,1,1]
	v_pk_fma_f32 v[14:15], v[196:197], v[46:47], v[14:15] op_sel_hi:[0,1,1]
	v_fmac_f32_e32 v20, v196, v55
	s_waitcnt vmcnt(57)
	v_pk_fma_f32 v[10:11], v[198:199], v[50:51], v[10:11] op_sel_hi:[0,1,1]
	v_pk_fma_f32 v[12:13], v[198:199], v[26:27], v[12:13] op_sel_hi:[0,1,1]
	v_pk_fma_f32 v[16:17], v[198:199], v[34:35], v[16:17] op_sel_hi:[0,1,1]
	v_pk_fma_f32 v[14:15], v[198:199], v[42:43], v[14:15] op_sel_hi:[0,1,1]
	v_fmac_f32_e32 v20, v198, v56
	s_waitcnt vmcnt(56)
	v_pk_fma_f32 v[10:11], v[200:201], v[24:25], v[10:11] op_sel_hi:[0,1,1]
	v_pk_fma_f32 v[12:13], v[200:201], v[32:33], v[12:13] op_sel_hi:[0,1,1]
	v_pk_fma_f32 v[16:17], v[200:201], v[40:41], v[16:17] op_sel_hi:[0,1,1]
	v_pk_fma_f32 v[14:15], v[200:201], v[48:49], v[14:15] op_sel_hi:[0,1,1]
	v_fmac_f32_e32 v20, v200, v57
	global_load_dword v194, v[238:239], off
	v_lshl_add_u64 v[238:239], v[238:239], 0, s[46:47]
	global_load_dword v196, v[238:239], off
	v_lshl_add_u64 v[238:239], v[238:239], 0, s[46:47]
	global_load_dword v198, v[238:239], off
	v_lshl_add_u64 v[238:239], v[238:239], 0, s[46:47]
	global_load_dword v200, v[238:239], off
	v_lshl_add_u64 v[238:239], v[238:239], 0, s[46:47]
	ds_read_b128 v[22:25], v5 offset:4096
	ds_read_b128 v[26:29], v5 offset:8192
	ds_read_b128 v[30:33], v5 offset:12288
	ds_read_b128 v[34:37], v5 offset:16384
	ds_read_b128 v[38:41], v5 offset:20480
	ds_read_b128 v[42:45], v5 offset:24576
	ds_read_b128 v[46:49], v5 offset:28672
	ds_read_b128 v[50:53], v5
	ds_read_b128 v[54:57], v5 offset:32768
	s_waitcnt lgkmcnt(8)
	v_mov_b32_e32 v67, v22
	v_add_u32_e32 v5, 16, v5
	s_waitcnt lgkmcnt(1)
	v_mov_b32_e32 v66, v50
	v_mov_b32_e32 v22, v51
	v_mov_b32_e32 v50, v52
	v_mov_b32_e32 v51, v24
	v_mov_b32_e32 v24, v53
	v_mov_b32_e32 v52, v26
	v_mov_b32_e32 v53, v30
	v_mov_b32_e32 v30, v27
	v_mov_b32_e32 v26, v28
	v_mov_b32_e32 v27, v32
	v_mov_b32_e32 v32, v29
	v_mov_b32_e32 v28, v34
	v_mov_b32_e32 v29, v38
	v_mov_b32_e32 v38, v35
	v_mov_b32_e32 v34, v36
	v_mov_b32_e32 v35, v40
	v_mov_b32_e32 v40, v37
	v_mov_b32_e32 v36, v42
	v_mov_b32_e32 v37, v46
	v_mov_b32_e32 v46, v43
	v_mov_b32_e32 v42, v44
	v_mov_b32_e32 v43, v48
	v_mov_b32_e32 v48, v45
	s_waitcnt vmcnt(59)
	v_pk_fma_f32 v[10:11], v[202:203], v[66:67], v[10:11] op_sel_hi:[0,1,1]
	v_pk_fma_f32 v[12:13], v[202:203], v[52:53], v[12:13] op_sel_hi:[0,1,1]
	v_pk_fma_f32 v[16:17], v[202:203], v[28:29], v[16:17] op_sel_hi:[0,1,1]
	v_pk_fma_f32 v[14:15], v[202:203], v[36:37], v[14:15] op_sel_hi:[0,1,1]
	s_waitcnt lgkmcnt(0)
	v_fmac_f32_e32 v20, v202, v54
	s_waitcnt vmcnt(58)
	v_pk_fma_f32 v[10:11], v[204:205], v[22:23], v[10:11] op_sel_hi:[0,1,1]
	v_pk_fma_f32 v[12:13], v[204:205], v[30:31], v[12:13] op_sel_hi:[0,1,1]
	v_pk_fma_f32 v[16:17], v[204:205], v[38:39], v[16:17] op_sel_hi:[0,1,1]
	v_pk_fma_f32 v[14:15], v[204:205], v[46:47], v[14:15] op_sel_hi:[0,1,1]
	v_fmac_f32_e32 v20, v204, v55
	s_waitcnt vmcnt(57)
	v_pk_fma_f32 v[10:11], v[206:207], v[50:51], v[10:11] op_sel_hi:[0,1,1]
	v_pk_fma_f32 v[12:13], v[206:207], v[26:27], v[12:13] op_sel_hi:[0,1,1]
	v_pk_fma_f32 v[16:17], v[206:207], v[34:35], v[16:17] op_sel_hi:[0,1,1]
	v_pk_fma_f32 v[14:15], v[206:207], v[42:43], v[14:15] op_sel_hi:[0,1,1]
	v_fmac_f32_e32 v20, v206, v56
	s_waitcnt vmcnt(56)
	v_pk_fma_f32 v[10:11], v[208:209], v[24:25], v[10:11] op_sel_hi:[0,1,1]
	v_pk_fma_f32 v[12:13], v[208:209], v[32:33], v[12:13] op_sel_hi:[0,1,1]
	v_pk_fma_f32 v[16:17], v[208:209], v[40:41], v[16:17] op_sel_hi:[0,1,1]
	v_pk_fma_f32 v[14:15], v[208:209], v[48:49], v[14:15] op_sel_hi:[0,1,1]
	v_fmac_f32_e32 v20, v208, v57
	global_load_dword v202, v[238:239], off
	v_lshl_add_u64 v[238:239], v[238:239], 0, s[46:47]
	global_load_dword v204, v[238:239], off
	v_lshl_add_u64 v[238:239], v[238:239], 0, s[46:47]
	global_load_dword v206, v[238:239], off
	v_lshl_add_u64 v[238:239], v[238:239], 0, s[46:47]
	global_load_dword v208, v[238:239], off
	v_lshl_add_u64 v[238:239], v[238:239], 0, s[46:47]
	ds_read_b128 v[22:25], v5 offset:4096
	ds_read_b128 v[26:29], v5 offset:8192
	ds_read_b128 v[30:33], v5 offset:12288
	ds_read_b128 v[34:37], v5 offset:16384
	ds_read_b128 v[38:41], v5 offset:20480
	ds_read_b128 v[42:45], v5 offset:24576
	ds_read_b128 v[46:49], v5 offset:28672
	ds_read_b128 v[50:53], v5
	ds_read_b128 v[54:57], v5 offset:32768
	s_waitcnt lgkmcnt(8)
	v_mov_b32_e32 v67, v22
	v_add_u32_e32 v5, 16, v5
	s_waitcnt lgkmcnt(1)
; DI void mod_item(const KP& P, int l, int nc, LAS float* S  , LAS float* red  ) {
;     ...
;         const float* w = P.w_mod + (size_t)l * D * 6144 + n0 + col;
; #pragma unroll 4
;         for (int k = kq * 128; k < kq * 128 + 128; ++k) { const float wv = w[(size_t)k * 6144];
; #pragma unroll
;             for (int r = 0; r < 9; ++r) a[r] += S[r * D + k] * wv; }
	v_mov_b32_e32 v66, v50
	v_mov_b32_e32 v22, v51
	v_mov_b32_e32 v50, v52
	v_mov_b32_e32 v51, v24
	v_mov_b32_e32 v24, v53
	v_mov_b32_e32 v52, v26
	v_mov_b32_e32 v53, v30
	v_mov_b32_e32 v30, v27
	v_mov_b32_e32 v26, v28
	v_mov_b32_e32 v27, v32
	v_mov_b32_e32 v32, v29
	v_mov_b32_e32 v28, v34
	v_mov_b32_e32 v29, v38
	v_mov_b32_e32 v38, v35
	v_mov_b32_e32 v34, v36
	v_mov_b32_e32 v35, v40
	v_mov_b32_e32 v40, v37
	v_mov_b32_e32 v36, v42
	v_mov_b32_e32 v37, v46
	v_mov_b32_e32 v46, v43
	v_mov_b32_e32 v42, v44
	v_mov_b32_e32 v43, v48
	v_mov_b32_e32 v48, v45
	s_waitcnt vmcnt(59)
	v_pk_fma_f32 v[10:11], v[210:211], v[66:67], v[10:11] op_sel_hi:[0,1,1]
	v_pk_fma_f32 v[12:13], v[210:211], v[52:53], v[12:13] op_sel_hi:[0,1,1]
	v_pk_fma_f32 v[16:17], v[210:211], v[28:29], v[16:17] op_sel_hi:[0,1,1]
	v_pk_fma_f32 v[14:15], v[210:211], v[36:37], v[14:15] op_sel_hi:[0,1,1]
	s_waitcnt lgkmcnt(0)
	v_fmac_f32_e32 v20, v210, v54
	s_waitcnt vmcnt(58)
	v_pk_fma_f32 v[10:11], v[212:213], v[22:23], v[10:11] op_sel_hi:[0,1,1]
	v_pk_fma_f32 v[12:13], v[212:213], v[30:31], v[12:13] op_sel_hi:[0,1,1]
	v_pk_fma_f32 v[16:17], v[212:213], v[38:39], v[16:17] op_sel_hi:[0,1,1]
	v_pk_fma_f32 v[14:15], v[212:213], v[46:47], v[14:15] op_sel_hi:[0,1,1]
	v_fmac_f32_e32 v20, v212, v55
	s_waitcnt vmcnt(57)
	v_pk_fma_f32 v[10:11], v[214:215], v[50:51], v[10:11] op_sel_hi:[0,1,1]
	v_pk_fma_f32 v[12:13], v[214:215], v[26:27], v[12:13] op_sel_hi:[0,1,1]
	v_pk_fma_f32 v[16:17], v[214:215], v[34:35], v[16:17] op_sel_hi:[0,1,1]
	v_pk_fma_f32 v[14:15], v[214:215], v[42:43], v[14:15] op_sel_hi:[0,1,1]
	v_fmac_f32_e32 v20, v214, v56
	s_waitcnt vmcnt(56)
	v_pk_fma_f32 v[10:11], v[216:217], v[24:25], v[10:11] op_sel_hi:[0,1,1]
	v_pk_fma_f32 v[12:13], v[216:217], v[32:33], v[12:13] op_sel_hi:[0,1,1]
	v_pk_fma_f32 v[16:17], v[216:217], v[40:41], v[16:17] op_sel_hi:[0,1,1]
	v_pk_fma_f32 v[14:15], v[216:217], v[48:49], v[14:15] op_sel_hi:[0,1,1]
	v_fmac_f32_e32 v20, v216, v57
	global_load_dword v210, v[238:239], off
	v_lshl_add_u64 v[238:239], v[238:239], 0, s[46:47]
	global_load_dword v212, v[238:239], off
	v_lshl_add_u64 v[238:239], v[238:239], 0, s[46:47]
	global_load_dword v214, v[238:239], off
	v_lshl_add_u64 v[238:239], v[238:239], 0, s[46:47]
	global_load_dword v216, v[238:239], off
	v_lshl_add_u64 v[238:239], v[238:239], 0, s[46:47]
	ds_read_b128 v[22:25], v5 offset:4096
	ds_read_b128 v[26:29], v5 offset:8192
	ds_read_b128 v[30:33], v5 offset:12288
	ds_read_b128 v[34:37], v5 offset:16384
	ds_read_b128 v[38:41], v5 offset:20480
	ds_read_b128 v[42:45], v5 offset:24576
	ds_read_b128 v[46:49], v5 offset:28672
	ds_read_b128 v[50:53], v5
	ds_read_b128 v[54:57], v5 offset:32768
	s_waitcnt lgkmcnt(8)
	v_mov_b32_e32 v67, v22
	v_add_u32_e32 v5, 16, v5
	s_waitcnt lgkmcnt(1)
	v_mov_b32_e32 v66, v50
	v_mov_b32_e32 v22, v51
	v_mov_b32_e32 v50, v52
	v_mov_b32_e32 v51, v24
	v_mov_b32_e32 v24, v53
	v_mov_b32_e32 v52, v26
	v_mov_b32_e32 v53, v30
	v_mov_b32_e32 v30, v27
	v_mov_b32_e32 v26, v28
	v_mov_b32_e32 v27, v32
	v_mov_b32_e32 v32, v29
	v_mov_b32_e32 v28, v34
	v_mov_b32_e32 v29, v38
	v_mov_b32_e32 v38, v35
	v_mov_b32_e32 v34, v36
	v_mov_b32_e32 v35, v40
	v_mov_b32_e32 v40, v37
	v_mov_b32_e32 v36, v42
	v_mov_b32_e32 v37, v46
	v_mov_b32_e32 v46, v43
	v_mov_b32_e32 v42, v44
	v_mov_b32_e32 v43, v48
	v_mov_b32_e32 v48, v45
	s_waitcnt vmcnt(59)
	v_pk_fma_f32 v[10:11], v[218:219], v[66:67], v[10:11] op_sel_hi:[0,1,1]
	v_pk_fma_f32 v[12:13], v[218:219], v[52:53], v[12:13] op_sel_hi:[0,1,1]
	v_pk_fma_f32 v[16:17], v[218:219], v[28:29], v[16:17] op_sel_hi:[0,1,1]
	v_pk_fma_f32 v[14:15], v[218:219], v[36:37], v[14:15] op_sel_hi:[0,1,1]
	s_waitcnt lgkmcnt(0)
	v_fmac_f32_e32 v20, v218, v54
	s_waitcnt vmcnt(58)
	v_pk_fma_f32 v[10:11], v[220:221], v[22:23], v[10:11] op_sel_hi:[0,1,1]
	v_pk_fma_f32 v[12:13], v[220:221], v[30:31], v[12:13] op_sel_hi:[0,1,1]
	v_pk_fma_f32 v[16:17], v[220:221], v[38:39], v[16:17] op_sel_hi:[0,1,1]
	v_pk_fma_f32 v[14:15], v[220:221], v[46:47], v[14:15] op_sel_hi:[0,1,1]
	v_fmac_f32_e32 v20, v220, v55
	s_waitcnt vmcnt(57)
	v_pk_fma_f32 v[10:11], v[222:223], v[50:51], v[10:11] op_sel_hi:[0,1,1]
	v_pk_fma_f32 v[12:13], v[222:223], v[26:27], v[12:13] op_sel_hi:[0,1,1]
	v_pk_fma_f32 v[16:17], v[222:223], v[34:35], v[16:17] op_sel_hi:[0,1,1]
	v_pk_fma_f32 v[14:15], v[222:223], v[42:43], v[14:15] op_sel_hi:[0,1,1]
	v_fmac_f32_e32 v20, v222, v56
	s_waitcnt vmcnt(56)
	v_pk_fma_f32 v[10:11], v[224:225], v[24:25], v[10:11] op_sel_hi:[0,1,1]
	v_pk_fma_f32 v[12:13], v[224:225], v[32:33], v[12:13] op_sel_hi:[0,1,1]
	v_pk_fma_f32 v[16:17], v[224:225], v[40:41], v[16:17] op_sel_hi:[0,1,1]
	v_pk_fma_f32 v[14:15], v[224:225], v[48:49], v[14:15] op_sel_hi:[0,1,1]
	v_fmac_f32_e32 v20, v224, v57
	global_load_dword v218, v[238:239], off
	v_lshl_add_u64 v[238:239], v[238:239], 0, s[46:47]
	global_load_dword v220, v[238:239], off
	v_lshl_add_u64 v[238:239], v[238:239], 0, s[46:47]
	global_load_dword v222, v[238:239], off
	v_lshl_add_u64 v[238:239], v[238:239], 0, s[46:47]
	global_load_dword v224, v[238:239], off
	v_lshl_add_u64 v[238:239], v[238:239], 0, s[46:47]
	ds_read_b128 v[22:25], v5 offset:4096
	ds_read_b128 v[26:29], v5 offset:8192
	ds_read_b128 v[30:33], v5 offset:12288
	ds_read_b128 v[34:37], v5 offset:16384
	ds_read_b128 v[38:41], v5 offset:20480
	ds_read_b128 v[42:45], v5 offset:24576
	ds_read_b128 v[46:49], v5 offset:28672
	ds_read_b128 v[50:53], v5
	ds_read_b128 v[54:57], v5 offset:32768
	s_waitcnt lgkmcnt(8)
	v_mov_b32_e32 v67, v22
	v_add_u32_e32 v5, 16, v5
	s_waitcnt lgkmcnt(1)
; DI void mod_item(const KP& P, int l, int nc, LAS float* S  , LAS float* red  ) {
;     ...
;         const float* w = P.w_mod + (size_t)l * D * 6144 + n0 + col;
; #pragma unroll 4
;         for (int k = kq * 128; k < kq * 128 + 128; ++k) { const float wv = w[(size_t)k * 6144];
; #pragma unroll
;             for (int r = 0; r < 9; ++r) a[r] += S[r * D + k] * wv; }
	v_mov_b32_e32 v66, v50
	v_mov_b32_e32 v22, v51
	v_mov_b32_e32 v50, v52
	v_mov_b32_e32 v51, v24
	v_mov_b32_e32 v24, v53
	v_mov_b32_e32 v52, v26
	v_mov_b32_e32 v53, v30
	v_mov_b32_e32 v30, v27
	v_mov_b32_e32 v26, v28
	v_mov_b32_e32 v27, v32
	v_mov_b32_e32 v32, v29
	v_mov_b32_e32 v28, v34
	v_mov_b32_e32 v29, v38
	v_mov_b32_e32 v38, v35
	v_mov_b32_e32 v34, v36
	v_mov_b32_e32 v35, v40
	v_mov_b32_e32 v40, v37
	v_mov_b32_e32 v36, v42
	v_mov_b32_e32 v37, v46
	v_mov_b32_e32 v46, v43
	v_mov_b32_e32 v42, v44
	v_mov_b32_e32 v43, v48
	v_mov_b32_e32 v48, v45
	s_waitcnt vmcnt(59)
	v_pk_fma_f32 v[10:11], v[226:227], v[66:67], v[10:11] op_sel_hi:[0,1,1]
	v_pk_fma_f32 v[12:13], v[226:227], v[52:53], v[12:13] op_sel_hi:[0,1,1]
	v_pk_fma_f32 v[16:17], v[226:227], v[28:29], v[16:17] op_sel_hi:[0,1,1]
	v_pk_fma_f32 v[14:15], v[226:227], v[36:37], v[14:15] op_sel_hi:[0,1,1]
	s_waitcnt lgkmcnt(0)
	v_fmac_f32_e32 v20, v226, v54
	s_waitcnt vmcnt(58)
	v_pk_fma_f32 v[10:11], v[228:229], v[22:23], v[10:11] op_sel_hi:[0,1,1]
	v_pk_fma_f32 v[12:13], v[228:229], v[30:31], v[12:13] op_sel_hi:[0,1,1]
	v_pk_fma_f32 v[16:17], v[228:229], v[38:39], v[16:17] op_sel_hi:[0,1,1]
	v_pk_fma_f32 v[14:15], v[228:229], v[46:47], v[14:15] op_sel_hi:[0,1,1]
	v_fmac_f32_e32 v20, v228, v55
	s_waitcnt vmcnt(57)
	v_pk_fma_f32 v[10:11], v[230:231], v[50:51], v[10:11] op_sel_hi:[0,1,1]
	v_pk_fma_f32 v[12:13], v[230:231], v[26:27], v[12:13] op_sel_hi:[0,1,1]
	v_pk_fma_f32 v[16:17], v[230:231], v[34:35], v[16:17] op_sel_hi:[0,1,1]
	v_pk_fma_f32 v[14:15], v[230:231], v[42:43], v[14:15] op_sel_hi:[0,1,1]
	v_fmac_f32_e32 v20, v230, v56
	s_waitcnt vmcnt(56)
	v_pk_fma_f32 v[10:11], v[232:233], v[24:25], v[10:11] op_sel_hi:[0,1,1]
	v_pk_fma_f32 v[12:13], v[232:233], v[32:33], v[12:13] op_sel_hi:[0,1,1]
	v_pk_fma_f32 v[16:17], v[232:233], v[40:41], v[16:17] op_sel_hi:[0,1,1]
	v_pk_fma_f32 v[14:15], v[232:233], v[48:49], v[14:15] op_sel_hi:[0,1,1]
	v_fmac_f32_e32 v20, v232, v57
	global_load_dword v226, v[238:239], off
	v_lshl_add_u64 v[238:239], v[238:239], 0, s[46:47]
	global_load_dword v228, v[238:239], off
	v_lshl_add_u64 v[238:239], v[238:239], 0, s[46:47]
	global_load_dword v230, v[238:239], off
	v_lshl_add_u64 v[238:239], v[238:239], 0, s[46:47]
	global_load_dword v232, v[238:239], off
	v_lshl_add_u64 v[238:239], v[238:239], 0, s[46:47]
	ds_read_b128 v[22:25], v5 offset:4096
	ds_read_b128 v[26:29], v5 offset:8192
	ds_read_b128 v[30:33], v5 offset:12288
	ds_read_b128 v[34:37], v5 offset:16384
	ds_read_b128 v[38:41], v5 offset:20480
	ds_read_b128 v[42:45], v5 offset:24576
	ds_read_b128 v[46:49], v5 offset:28672
	ds_read_b128 v[50:53], v5
	ds_read_b128 v[54:57], v5 offset:32768
	s_waitcnt lgkmcnt(8)
	v_mov_b32_e32 v67, v22
	v_add_u32_e32 v5, 16, v5
	s_waitcnt lgkmcnt(1)
	v_mov_b32_e32 v66, v50
	v_mov_b32_e32 v22, v51
	v_mov_b32_e32 v50, v52
	v_mov_b32_e32 v51, v24
	v_mov_b32_e32 v24, v53
	v_mov_b32_e32 v52, v26
	v_mov_b32_e32 v53, v30
	v_mov_b32_e32 v30, v27
	v_mov_b32_e32 v26, v28
	v_mov_b32_e32 v27, v32
	v_mov_b32_e32 v32, v29
	v_mov_b32_e32 v28, v34
	v_mov_b32_e32 v29, v38
	v_mov_b32_e32 v38, v35
	v_mov_b32_e32 v34, v36
	v_mov_b32_e32 v35, v40
	v_mov_b32_e32 v40, v37
	v_mov_b32_e32 v36, v42
	v_mov_b32_e32 v37, v46
	v_mov_b32_e32 v46, v43
	v_mov_b32_e32 v42, v44
	v_mov_b32_e32 v43, v48
	v_mov_b32_e32 v48, v45
	s_waitcnt vmcnt(59)
	v_pk_fma_f32 v[10:11], v[108:109], v[66:67], v[10:11] op_sel_hi:[0,1,1]
	v_pk_fma_f32 v[12:13], v[108:109], v[52:53], v[12:13] op_sel_hi:[0,1,1]
	v_pk_fma_f32 v[16:17], v[108:109], v[28:29], v[16:17] op_sel_hi:[0,1,1]
	v_pk_fma_f32 v[14:15], v[108:109], v[36:37], v[14:15] op_sel_hi:[0,1,1]
	s_waitcnt lgkmcnt(0)
	v_fmac_f32_e32 v20, v108, v54
	s_waitcnt vmcnt(58)
	v_pk_fma_f32 v[10:11], v[110:111], v[22:23], v[10:11] op_sel_hi:[0,1,1]
	v_pk_fma_f32 v[12:13], v[110:111], v[30:31], v[12:13] op_sel_hi:[0,1,1]
	v_pk_fma_f32 v[16:17], v[110:111], v[38:39], v[16:17] op_sel_hi:[0,1,1]
	v_pk_fma_f32 v[14:15], v[110:111], v[46:47], v[14:15] op_sel_hi:[0,1,1]
	v_fmac_f32_e32 v20, v110, v55
	s_waitcnt vmcnt(57)
	v_pk_fma_f32 v[10:11], v[112:113], v[50:51], v[10:11] op_sel_hi:[0,1,1]
	v_pk_fma_f32 v[12:13], v[112:113], v[26:27], v[12:13] op_sel_hi:[0,1,1]
	v_pk_fma_f32 v[16:17], v[112:113], v[34:35], v[16:17] op_sel_hi:[0,1,1]
	v_pk_fma_f32 v[14:15], v[112:113], v[42:43], v[14:15] op_sel_hi:[0,1,1]
	v_fmac_f32_e32 v20, v112, v56
	s_waitcnt vmcnt(56)
	v_pk_fma_f32 v[10:11], v[114:115], v[24:25], v[10:11] op_sel_hi:[0,1,1]
	v_pk_fma_f32 v[12:13], v[114:115], v[32:33], v[12:13] op_sel_hi:[0,1,1]
	v_pk_fma_f32 v[16:17], v[114:115], v[40:41], v[16:17] op_sel_hi:[0,1,1]
	v_pk_fma_f32 v[14:15], v[114:115], v[48:49], v[14:15] op_sel_hi:[0,1,1]
	v_fmac_f32_e32 v20, v114, v57
	global_load_dword v108, v[238:239], off
	v_lshl_add_u64 v[238:239], v[238:239], 0, s[46:47]
	global_load_dword v110, v[238:239], off
	v_lshl_add_u64 v[238:239], v[238:239], 0, s[46:47]
	global_load_dword v112, v[238:239], off
	v_lshl_add_u64 v[238:239], v[238:239], 0, s[46:47]
	global_load_dword v114, v[238:239], off
	v_lshl_add_u64 v[238:239], v[238:239], 0, s[46:47]
	ds_read_b128 v[22:25], v5 offset:4096
	ds_read_b128 v[26:29], v5 offset:8192
	ds_read_b128 v[30:33], v5 offset:12288
	ds_read_b128 v[34:37], v5 offset:16384
	ds_read_b128 v[38:41], v5 offset:20480
	ds_read_b128 v[42:45], v5 offset:24576
	ds_read_b128 v[46:49], v5 offset:28672
	ds_read_b128 v[50:53], v5
	ds_read_b128 v[54:57], v5 offset:32768
	s_waitcnt lgkmcnt(8)
	v_mov_b32_e32 v67, v22
	v_add_u32_e32 v5, 16, v5
	s_waitcnt lgkmcnt(1)
; DI void mod_item(const KP& P, int l, int nc, LAS float* S  , LAS float* red  ) {
;     ...
;         const float* w = P.w_mod + (size_t)l * D * 6144 + n0 + col;
; #pragma unroll 4
;         for (int k = kq * 128; k < kq * 128 + 128; ++k) { const float wv = w[(size_t)k * 6144];
; #pragma unroll
;             for (int r = 0; r < 9; ++r) a[r] += S[r * D + k] * wv; }
	v_mov_b32_e32 v66, v50
	v_mov_b32_e32 v22, v51
	v_mov_b32_e32 v50, v52
	v_mov_b32_e32 v51, v24
	v_mov_b32_e32 v24, v53
	v_mov_b32_e32 v52, v26
	v_mov_b32_e32 v53, v30
	v_mov_b32_e32 v30, v27
	v_mov_b32_e32 v26, v28
	v_mov_b32_e32 v27, v32
	v_mov_b32_e32 v32, v29
	v_mov_b32_e32 v28, v34
	v_mov_b32_e32 v29, v38
	v_mov_b32_e32 v38, v35
	v_mov_b32_e32 v34, v36
	v_mov_b32_e32 v35, v40
	v_mov_b32_e32 v40, v37
	v_mov_b32_e32 v36, v42
	v_mov_b32_e32 v37, v46
	v_mov_b32_e32 v46, v43
	v_mov_b32_e32 v42, v44
	v_mov_b32_e32 v43, v48
	v_mov_b32_e32 v48, v45
	s_waitcnt vmcnt(59)
	v_pk_fma_f32 v[10:11], v[116:117], v[66:67], v[10:11] op_sel_hi:[0,1,1]
	v_pk_fma_f32 v[12:13], v[116:117], v[52:53], v[12:13] op_sel_hi:[0,1,1]
	v_pk_fma_f32 v[16:17], v[116:117], v[28:29], v[16:17] op_sel_hi:[0,1,1]
	v_pk_fma_f32 v[14:15], v[116:117], v[36:37], v[14:15] op_sel_hi:[0,1,1]
	s_waitcnt lgkmcnt(0)
	v_fmac_f32_e32 v20, v116, v54
	s_waitcnt vmcnt(58)
	v_pk_fma_f32 v[10:11], v[118:119], v[22:23], v[10:11] op_sel_hi:[0,1,1]
	v_pk_fma_f32 v[12:13], v[118:119], v[30:31], v[12:13] op_sel_hi:[0,1,1]
	v_pk_fma_f32 v[16:17], v[118:119], v[38:39], v[16:17] op_sel_hi:[0,1,1]
	v_pk_fma_f32 v[14:15], v[118:119], v[46:47], v[14:15] op_sel_hi:[0,1,1]
	v_fmac_f32_e32 v20, v118, v55
	s_waitcnt vmcnt(57)
	v_pk_fma_f32 v[10:11], v[120:121], v[50:51], v[10:11] op_sel_hi:[0,1,1]
	v_pk_fma_f32 v[12:13], v[120:121], v[26:27], v[12:13] op_sel_hi:[0,1,1]
	v_pk_fma_f32 v[16:17], v[120:121], v[34:35], v[16:17] op_sel_hi:[0,1,1]
	v_pk_fma_f32 v[14:15], v[120:121], v[42:43], v[14:15] op_sel_hi:[0,1,1]
	v_fmac_f32_e32 v20, v120, v56
	s_waitcnt vmcnt(56)
	v_pk_fma_f32 v[10:11], v[122:123], v[24:25], v[10:11] op_sel_hi:[0,1,1]
	v_pk_fma_f32 v[12:13], v[122:123], v[32:33], v[12:13] op_sel_hi:[0,1,1]
	v_pk_fma_f32 v[16:17], v[122:123], v[40:41], v[16:17] op_sel_hi:[0,1,1]
	v_pk_fma_f32 v[14:15], v[122:123], v[48:49], v[14:15] op_sel_hi:[0,1,1]
	v_fmac_f32_e32 v20, v122, v57
	global_load_dword v116, v[238:239], off
	v_lshl_add_u64 v[238:239], v[238:239], 0, s[46:47]
	global_load_dword v118, v[238:239], off
	v_lshl_add_u64 v[238:239], v[238:239], 0, s[46:47]
	global_load_dword v120, v[238:239], off
	v_lshl_add_u64 v[238:239], v[238:239], 0, s[46:47]
	global_load_dword v122, v[238:239], off
	v_lshl_add_u64 v[238:239], v[238:239], 0, s[46:47]
	ds_read_b128 v[22:25], v5 offset:4096
	ds_read_b128 v[26:29], v5 offset:8192
	ds_read_b128 v[30:33], v5 offset:12288
	ds_read_b128 v[34:37], v5 offset:16384
	ds_read_b128 v[38:41], v5 offset:20480
	ds_read_b128 v[42:45], v5 offset:24576
	ds_read_b128 v[46:49], v5 offset:28672
	ds_read_b128 v[50:53], v5
	ds_read_b128 v[54:57], v5 offset:32768
	s_waitcnt lgkmcnt(8)
	v_mov_b32_e32 v67, v22
	v_add_u32_e32 v5, 16, v5
	s_waitcnt lgkmcnt(1)
	v_mov_b32_e32 v66, v50
	v_mov_b32_e32 v22, v51
	v_mov_b32_e32 v50, v52
	v_mov_b32_e32 v51, v24
	v_mov_b32_e32 v24, v53
	v_mov_b32_e32 v52, v26
	v_mov_b32_e32 v53, v30
	v_mov_b32_e32 v30, v27
	v_mov_b32_e32 v26, v28
	v_mov_b32_e32 v27, v32
	v_mov_b32_e32 v32, v29
	v_mov_b32_e32 v28, v34
	v_mov_b32_e32 v29, v38
	v_mov_b32_e32 v38, v35
	v_mov_b32_e32 v34, v36
	v_mov_b32_e32 v35, v40
	v_mov_b32_e32 v40, v37
	v_mov_b32_e32 v36, v42
	v_mov_b32_e32 v37, v46
	v_mov_b32_e32 v46, v43
	v_mov_b32_e32 v42, v44
	v_mov_b32_e32 v43, v48
	v_mov_b32_e32 v48, v45
	s_waitcnt vmcnt(59)
	v_pk_fma_f32 v[10:11], v[124:125], v[66:67], v[10:11] op_sel_hi:[0,1,1]
	v_pk_fma_f32 v[12:13], v[124:125], v[52:53], v[12:13] op_sel_hi:[0,1,1]
	v_pk_fma_f32 v[16:17], v[124:125], v[28:29], v[16:17] op_sel_hi:[0,1,1]
	v_pk_fma_f32 v[14:15], v[124:125], v[36:37], v[14:15] op_sel_hi:[0,1,1]
	s_waitcnt lgkmcnt(0)
	v_fmac_f32_e32 v20, v124, v54
	s_waitcnt vmcnt(58)
	v_pk_fma_f32 v[10:11], v[126:127], v[22:23], v[10:11] op_sel_hi:[0,1,1]
	v_pk_fma_f32 v[12:13], v[126:127], v[30:31], v[12:13] op_sel_hi:[0,1,1]
	v_pk_fma_f32 v[16:17], v[126:127], v[38:39], v[16:17] op_sel_hi:[0,1,1]
	v_pk_fma_f32 v[14:15], v[126:127], v[46:47], v[14:15] op_sel_hi:[0,1,1]
	v_fmac_f32_e32 v20, v126, v55
	s_waitcnt vmcnt(57)
	v_pk_fma_f32 v[10:11], v[128:129], v[50:51], v[10:11] op_sel_hi:[0,1,1]
	v_pk_fma_f32 v[12:13], v[128:129], v[26:27], v[12:13] op_sel_hi:[0,1,1]
	v_pk_fma_f32 v[16:17], v[128:129], v[34:35], v[16:17] op_sel_hi:[0,1,1]
	v_pk_fma_f32 v[14:15], v[128:129], v[42:43], v[14:15] op_sel_hi:[0,1,1]
	v_fmac_f32_e32 v20, v128, v56
	s_waitcnt vmcnt(56)
	v_pk_fma_f32 v[10:11], v[130:131], v[24:25], v[10:11] op_sel_hi:[0,1,1]
	v_pk_fma_f32 v[12:13], v[130:131], v[32:33], v[12:13] op_sel_hi:[0,1,1]
	v_pk_fma_f32 v[16:17], v[130:131], v[40:41], v[16:17] op_sel_hi:[0,1,1]
	v_pk_fma_f32 v[14:15], v[130:131], v[48:49], v[14:15] op_sel_hi:[0,1,1]
	v_fmac_f32_e32 v20, v130, v57
	ds_read_b128 v[22:25], v5 offset:4096
	ds_read_b128 v[26:29], v5 offset:8192
	ds_read_b128 v[30:33], v5 offset:12288
	ds_read_b128 v[34:37], v5 offset:16384
	ds_read_b128 v[38:41], v5 offset:20480
	ds_read_b128 v[42:45], v5 offset:24576
	ds_read_b128 v[46:49], v5 offset:28672
	ds_read_b128 v[50:53], v5
	ds_read_b128 v[54:57], v5 offset:32768
	s_waitcnt lgkmcnt(8)
	v_mov_b32_e32 v67, v22
	v_add_u32_e32 v5, 16, v5
	s_waitcnt lgkmcnt(1)
	v_mov_b32_e32 v66, v50
	v_mov_b32_e32 v22, v51
	v_mov_b32_e32 v50, v52
	v_mov_b32_e32 v51, v24
	v_mov_b32_e32 v24, v53
	v_mov_b32_e32 v52, v26
	v_mov_b32_e32 v53, v30
	v_mov_b32_e32 v30, v27
	v_mov_b32_e32 v26, v28
	v_mov_b32_e32 v27, v32
	v_mov_b32_e32 v32, v29
	v_mov_b32_e32 v28, v34
	v_mov_b32_e32 v29, v38
	v_mov_b32_e32 v38, v35
	v_mov_b32_e32 v34, v36
	v_mov_b32_e32 v35, v40
	v_mov_b32_e32 v40, v37
	v_mov_b32_e32 v36, v42
	v_mov_b32_e32 v37, v46
	v_mov_b32_e32 v46, v43
	v_mov_b32_e32 v42, v44
	v_mov_b32_e32 v43, v48
	v_mov_b32_e32 v48, v45
	s_waitcnt vmcnt(55)
; DI void mod_item(const KP& P, int l, int nc, LAS float* S  , LAS float* red  ) {
;     ...
;         const float* w = P.w_mod + (size_t)l * D * 6144 + n0 + col;
; #pragma unroll 4
;         for (int k = kq * 128; k < kq * 128 + 128; ++k) { const float wv = w[(size_t)k * 6144];
; #pragma unroll
;             for (int r = 0; r < 9; ++r) a[r] += S[r * D + k] * wv; }
	v_pk_fma_f32 v[10:11], v[132:133], v[66:67], v[10:11] op_sel_hi:[0,1,1]
	v_pk_fma_f32 v[12:13], v[132:133], v[52:53], v[12:13] op_sel_hi:[0,1,1]
	v_pk_fma_f32 v[16:17], v[132:133], v[28:29], v[16:17] op_sel_hi:[0,1,1]
	v_pk_fma_f32 v[14:15], v[132:133], v[36:37], v[14:15] op_sel_hi:[0,1,1]
	s_waitcnt lgkmcnt(0)
	v_fmac_f32_e32 v20, v132, v54
	s_waitcnt vmcnt(54)
	v_pk_fma_f32 v[10:11], v[134:135], v[22:23], v[10:11] op_sel_hi:[0,1,1]
	v_pk_fma_f32 v[12:13], v[134:135], v[30:31], v[12:13] op_sel_hi:[0,1,1]
	v_pk_fma_f32 v[16:17], v[134:135], v[38:39], v[16:17] op_sel_hi:[0,1,1]
	v_pk_fma_f32 v[14:15], v[134:135], v[46:47], v[14:15] op_sel_hi:[0,1,1]
	v_fmac_f32_e32 v20, v134, v55
	s_waitcnt vmcnt(53)
	v_pk_fma_f32 v[10:11], v[136:137], v[50:51], v[10:11] op_sel_hi:[0,1,1]
	v_pk_fma_f32 v[12:13], v[136:137], v[26:27], v[12:13] op_sel_hi:[0,1,1]
	v_pk_fma_f32 v[16:17], v[136:137], v[34:35], v[16:17] op_sel_hi:[0,1,1]
	v_pk_fma_f32 v[14:15], v[136:137], v[42:43], v[14:15] op_sel_hi:[0,1,1]
	v_fmac_f32_e32 v20, v136, v56
	s_waitcnt vmcnt(52)
	v_pk_fma_f32 v[10:11], v[138:139], v[24:25], v[10:11] op_sel_hi:[0,1,1]
	v_pk_fma_f32 v[12:13], v[138:139], v[32:33], v[12:13] op_sel_hi:[0,1,1]
	v_pk_fma_f32 v[16:17], v[138:139], v[40:41], v[16:17] op_sel_hi:[0,1,1]
	v_pk_fma_f32 v[14:15], v[138:139], v[48:49], v[14:15] op_sel_hi:[0,1,1]
	v_fmac_f32_e32 v20, v138, v57
	ds_read_b128 v[22:25], v5 offset:4096
	ds_read_b128 v[26:29], v5 offset:8192
	ds_read_b128 v[30:33], v5 offset:12288
	ds_read_b128 v[34:37], v5 offset:16384
	ds_read_b128 v[38:41], v5 offset:20480
	ds_read_b128 v[42:45], v5 offset:24576
	ds_read_b128 v[46:49], v5 offset:28672
	ds_read_b128 v[50:53], v5
	ds_read_b128 v[54:57], v5 offset:32768
	s_waitcnt lgkmcnt(8)
	v_mov_b32_e32 v67, v22
	v_add_u32_e32 v5, 16, v5
	s_waitcnt lgkmcnt(1)
	v_mov_b32_e32 v66, v50
	v_mov_b32_e32 v22, v51
	v_mov_b32_e32 v50, v52
	v_mov_b32_e32 v51, v24
	v_mov_b32_e32 v24, v53
	v_mov_b32_e32 v52, v26
	v_mov_b32_e32 v53, v30
	v_mov_b32_e32 v30, v27
	v_mov_b32_e32 v26, v28
	v_mov_b32_e32 v27, v32
	v_mov_b32_e32 v32, v29
	v_mov_b32_e32 v28, v34
	v_mov_b32_e32 v29, v38
	v_mov_b32_e32 v38, v35
	v_mov_b32_e32 v34, v36
	v_mov_b32_e32 v35, v40
	v_mov_b32_e32 v40, v37
	v_mov_b32_e32 v36, v42
	v_mov_b32_e32 v37, v46
	v_mov_b32_e32 v46, v43
	v_mov_b32_e32 v42, v44
	v_mov_b32_e32 v43, v48
	v_mov_b32_e32 v48, v45
	s_waitcnt vmcnt(51)
	v_pk_fma_f32 v[10:11], v[146:147], v[66:67], v[10:11] op_sel_hi:[0,1,1]
	v_pk_fma_f32 v[12:13], v[146:147], v[52:53], v[12:13] op_sel_hi:[0,1,1]
	v_pk_fma_f32 v[16:17], v[146:147], v[28:29], v[16:17] op_sel_hi:[0,1,1]
	v_pk_fma_f32 v[14:15], v[146:147], v[36:37], v[14:15] op_sel_hi:[0,1,1]
	s_waitcnt lgkmcnt(0)
	v_fmac_f32_e32 v20, v146, v54
	s_waitcnt vmcnt(50)
	v_pk_fma_f32 v[10:11], v[148:149], v[22:23], v[10:11] op_sel_hi:[0,1,1]
	v_pk_fma_f32 v[12:13], v[148:149], v[30:31], v[12:13] op_sel_hi:[0,1,1]
	v_pk_fma_f32 v[16:17], v[148:149], v[38:39], v[16:17] op_sel_hi:[0,1,1]
	v_pk_fma_f32 v[14:15], v[148:149], v[46:47], v[14:15] op_sel_hi:[0,1,1]
	v_fmac_f32_e32 v20, v148, v55
	s_waitcnt vmcnt(49)
	v_pk_fma_f32 v[10:11], v[150:151], v[50:51], v[10:11] op_sel_hi:[0,1,1]
	v_pk_fma_f32 v[12:13], v[150:151], v[26:27], v[12:13] op_sel_hi:[0,1,1]
	v_pk_fma_f32 v[16:17], v[150:151], v[34:35], v[16:17] op_sel_hi:[0,1,1]
	v_pk_fma_f32 v[14:15], v[150:151], v[42:43], v[14:15] op_sel_hi:[0,1,1]
	v_fmac_f32_e32 v20, v150, v56
	s_waitcnt vmcnt(48)
	v_pk_fma_f32 v[10:11], v[152:153], v[24:25], v[10:11] op_sel_hi:[0,1,1]
	v_pk_fma_f32 v[12:13], v[152:153], v[32:33], v[12:13] op_sel_hi:[0,1,1]
	v_pk_fma_f32 v[16:17], v[152:153], v[40:41], v[16:17] op_sel_hi:[0,1,1]
	v_pk_fma_f32 v[14:15], v[152:153], v[48:49], v[14:15] op_sel_hi:[0,1,1]
	v_fmac_f32_e32 v20, v152, v57
	ds_read_b128 v[22:25], v5 offset:4096
	ds_read_b128 v[26:29], v5 offset:8192
	ds_read_b128 v[30:33], v5 offset:12288
	ds_read_b128 v[34:37], v5 offset:16384
	ds_read_b128 v[38:41], v5 offset:20480
	ds_read_b128 v[42:45], v5 offset:24576
	ds_read_b128 v[46:49], v5 offset:28672
	ds_read_b128 v[50:53], v5
	ds_read_b128 v[54:57], v5 offset:32768
	s_waitcnt lgkmcnt(8)
	v_mov_b32_e32 v67, v22
	v_add_u32_e32 v5, 16, v5
	s_waitcnt lgkmcnt(1)
	v_mov_b32_e32 v66, v50
	v_mov_b32_e32 v22, v51
	v_mov_b32_e32 v50, v52
	v_mov_b32_e32 v51, v24
	v_mov_b32_e32 v24, v53
	v_mov_b32_e32 v52, v26
	v_mov_b32_e32 v53, v30
	v_mov_b32_e32 v30, v27
	v_mov_b32_e32 v26, v28
	v_mov_b32_e32 v27, v32
	v_mov_b32_e32 v32, v29
	v_mov_b32_e32 v28, v34
	v_mov_b32_e32 v29, v38
	v_mov_b32_e32 v38, v35
	v_mov_b32_e32 v34, v36
	v_mov_b32_e32 v35, v40
	v_mov_b32_e32 v40, v37
	v_mov_b32_e32 v36, v42
	v_mov_b32_e32 v37, v46
	v_mov_b32_e32 v46, v43
	v_mov_b32_e32 v42, v44
	v_mov_b32_e32 v43, v48
	v_mov_b32_e32 v48, v45
	s_waitcnt vmcnt(47)
	v_pk_fma_f32 v[10:11], v[154:155], v[66:67], v[10:11] op_sel_hi:[0,1,1]
	v_pk_fma_f32 v[12:13], v[154:155], v[52:53], v[12:13] op_sel_hi:[0,1,1]
	v_pk_fma_f32 v[16:17], v[154:155], v[28:29], v[16:17] op_sel_hi:[0,1,1]
	v_pk_fma_f32 v[14:15], v[154:155], v[36:37], v[14:15] op_sel_hi:[0,1,1]
	s_waitcnt lgkmcnt(0)
	v_fmac_f32_e32 v20, v154, v54
	s_waitcnt vmcnt(46)
	v_pk_fma_f32 v[10:11], v[156:157], v[22:23], v[10:11] op_sel_hi:[0,1,1]
	v_pk_fma_f32 v[12:13], v[156:157], v[30:31], v[12:13] op_sel_hi:[0,1,1]
	v_pk_fma_f32 v[16:17], v[156:157], v[38:39], v[16:17] op_sel_hi:[0,1,1]
	v_pk_fma_f32 v[14:15], v[156:157], v[46:47], v[14:15] op_sel_hi:[0,1,1]
	v_fmac_f32_e32 v20, v156, v55
	s_waitcnt vmcnt(45)
; DI void mod_item(const KP& P, int l, int nc, LAS float* S  , LAS float* red  ) {
;     ...
;         const float* w = P.w_mod + (size_t)l * D * 6144 + n0 + col;
; #pragma unroll 4
;         for (int k = kq * 128; k < kq * 128 + 128; ++k) { const float wv = w[(size_t)k * 6144];
; #pragma unroll
;             for (int r = 0; r < 9; ++r) a[r] += S[r * D + k] * wv; }
	v_pk_fma_f32 v[10:11], v[158:159], v[50:51], v[10:11] op_sel_hi:[0,1,1]
	v_pk_fma_f32 v[12:13], v[158:159], v[26:27], v[12:13] op_sel_hi:[0,1,1]
	v_pk_fma_f32 v[16:17], v[158:159], v[34:35], v[16:17] op_sel_hi:[0,1,1]
	v_pk_fma_f32 v[14:15], v[158:159], v[42:43], v[14:15] op_sel_hi:[0,1,1]
	v_fmac_f32_e32 v20, v158, v56
	s_waitcnt vmcnt(44)
	v_pk_fma_f32 v[10:11], v[160:161], v[24:25], v[10:11] op_sel_hi:[0,1,1]
	v_pk_fma_f32 v[12:13], v[160:161], v[32:33], v[12:13] op_sel_hi:[0,1,1]
	v_pk_fma_f32 v[16:17], v[160:161], v[40:41], v[16:17] op_sel_hi:[0,1,1]
	v_pk_fma_f32 v[14:15], v[160:161], v[48:49], v[14:15] op_sel_hi:[0,1,1]
	v_fmac_f32_e32 v20, v160, v57
	ds_read_b128 v[22:25], v5 offset:4096
	ds_read_b128 v[26:29], v5 offset:8192
	ds_read_b128 v[30:33], v5 offset:12288
	ds_read_b128 v[34:37], v5 offset:16384
	ds_read_b128 v[38:41], v5 offset:20480
	ds_read_b128 v[42:45], v5 offset:24576
	ds_read_b128 v[46:49], v5 offset:28672
	ds_read_b128 v[50:53], v5
	ds_read_b128 v[54:57], v5 offset:32768
	s_waitcnt lgkmcnt(8)
	v_mov_b32_e32 v67, v22
	v_add_u32_e32 v5, 16, v5
	s_waitcnt lgkmcnt(1)
	v_mov_b32_e32 v66, v50
	v_mov_b32_e32 v22, v51
	v_mov_b32_e32 v50, v52
	v_mov_b32_e32 v51, v24
	v_mov_b32_e32 v24, v53
	v_mov_b32_e32 v52, v26
	v_mov_b32_e32 v53, v30
	v_mov_b32_e32 v30, v27
	v_mov_b32_e32 v26, v28
	v_mov_b32_e32 v27, v32
	v_mov_b32_e32 v32, v29
	v_mov_b32_e32 v28, v34
	v_mov_b32_e32 v29, v38
	v_mov_b32_e32 v38, v35
	v_mov_b32_e32 v34, v36
	v_mov_b32_e32 v35, v40
	v_mov_b32_e32 v40, v37
	v_mov_b32_e32 v36, v42
	v_mov_b32_e32 v37, v46
	v_mov_b32_e32 v46, v43
	v_mov_b32_e32 v42, v44
	v_mov_b32_e32 v43, v48
	v_mov_b32_e32 v48, v45
	s_waitcnt vmcnt(43)
	v_pk_fma_f32 v[10:11], v[162:163], v[66:67], v[10:11] op_sel_hi:[0,1,1]
	v_pk_fma_f32 v[12:13], v[162:163], v[52:53], v[12:13] op_sel_hi:[0,1,1]
	v_pk_fma_f32 v[16:17], v[162:163], v[28:29], v[16:17] op_sel_hi:[0,1,1]
	v_pk_fma_f32 v[14:15], v[162:163], v[36:37], v[14:15] op_sel_hi:[0,1,1]
	s_waitcnt lgkmcnt(0)
	v_fmac_f32_e32 v20, v162, v54
	s_waitcnt vmcnt(42)
	v_pk_fma_f32 v[10:11], v[164:165], v[22:23], v[10:11] op_sel_hi:[0,1,1]
	v_pk_fma_f32 v[12:13], v[164:165], v[30:31], v[12:13] op_sel_hi:[0,1,1]
	v_pk_fma_f32 v[16:17], v[164:165], v[38:39], v[16:17] op_sel_hi:[0,1,1]
	v_pk_fma_f32 v[14:15], v[164:165], v[46:47], v[14:15] op_sel_hi:[0,1,1]
	v_fmac_f32_e32 v20, v164, v55
	s_waitcnt vmcnt(41)
	v_pk_fma_f32 v[10:11], v[166:167], v[50:51], v[10:11] op_sel_hi:[0,1,1]
	v_pk_fma_f32 v[12:13], v[166:167], v[26:27], v[12:13] op_sel_hi:[0,1,1]
	v_pk_fma_f32 v[16:17], v[166:167], v[34:35], v[16:17] op_sel_hi:[0,1,1]
	v_pk_fma_f32 v[14:15], v[166:167], v[42:43], v[14:15] op_sel_hi:[0,1,1]
	v_fmac_f32_e32 v20, v166, v56
	s_waitcnt vmcnt(40)
	v_pk_fma_f32 v[10:11], v[168:169], v[24:25], v[10:11] op_sel_hi:[0,1,1]
	v_pk_fma_f32 v[12:13], v[168:169], v[32:33], v[12:13] op_sel_hi:[0,1,1]
	v_pk_fma_f32 v[16:17], v[168:169], v[40:41], v[16:17] op_sel_hi:[0,1,1]
	v_pk_fma_f32 v[14:15], v[168:169], v[48:49], v[14:15] op_sel_hi:[0,1,1]
	v_fmac_f32_e32 v20, v168, v57
	ds_read_b128 v[22:25], v5 offset:4096
	ds_read_b128 v[26:29], v5 offset:8192
	ds_read_b128 v[30:33], v5 offset:12288
	ds_read_b128 v[34:37], v5 offset:16384
	ds_read_b128 v[38:41], v5 offset:20480
	ds_read_b128 v[42:45], v5 offset:24576
	ds_read_b128 v[46:49], v5 offset:28672
	ds_read_b128 v[50:53], v5
	ds_read_b128 v[54:57], v5 offset:32768
	s_waitcnt lgkmcnt(8)
	v_mov_b32_e32 v67, v22
	v_add_u32_e32 v5, 16, v5
	s_waitcnt lgkmcnt(1)
	v_mov_b32_e32 v66, v50
	v_mov_b32_e32 v22, v51
	v_mov_b32_e32 v50, v52
	v_mov_b32_e32 v51, v24
	v_mov_b32_e32 v24, v53
	v_mov_b32_e32 v52, v26
	v_mov_b32_e32 v53, v30
	v_mov_b32_e32 v30, v27
	v_mov_b32_e32 v26, v28
	v_mov_b32_e32 v27, v32
	v_mov_b32_e32 v32, v29
	v_mov_b32_e32 v28, v34
	v_mov_b32_e32 v29, v38
	v_mov_b32_e32 v38, v35
	v_mov_b32_e32 v34, v36
	v_mov_b32_e32 v35, v40
	v_mov_b32_e32 v40, v37
	v_mov_b32_e32 v36, v42
	v_mov_b32_e32 v37, v46
	v_mov_b32_e32 v46, v43
	v_mov_b32_e32 v42, v44
	v_mov_b32_e32 v43, v48
	v_mov_b32_e32 v48, v45
	s_waitcnt vmcnt(39)
	v_pk_fma_f32 v[10:11], v[170:171], v[66:67], v[10:11] op_sel_hi:[0,1,1]
	v_pk_fma_f32 v[12:13], v[170:171], v[52:53], v[12:13] op_sel_hi:[0,1,1]
	v_pk_fma_f32 v[16:17], v[170:171], v[28:29], v[16:17] op_sel_hi:[0,1,1]
	v_pk_fma_f32 v[14:15], v[170:171], v[36:37], v[14:15] op_sel_hi:[0,1,1]
	s_waitcnt lgkmcnt(0)
	v_fmac_f32_e32 v20, v170, v54
	s_waitcnt vmcnt(38)
	v_pk_fma_f32 v[10:11], v[172:173], v[22:23], v[10:11] op_sel_hi:[0,1,1]
	v_pk_fma_f32 v[12:13], v[172:173], v[30:31], v[12:13] op_sel_hi:[0,1,1]
	v_pk_fma_f32 v[16:17], v[172:173], v[38:39], v[16:17] op_sel_hi:[0,1,1]
	v_pk_fma_f32 v[14:15], v[172:173], v[46:47], v[14:15] op_sel_hi:[0,1,1]
	v_fmac_f32_e32 v20, v172, v55
	s_waitcnt vmcnt(37)
	v_pk_fma_f32 v[10:11], v[174:175], v[50:51], v[10:11] op_sel_hi:[0,1,1]
	v_pk_fma_f32 v[12:13], v[174:175], v[26:27], v[12:13] op_sel_hi:[0,1,1]
	v_pk_fma_f32 v[16:17], v[174:175], v[34:35], v[16:17] op_sel_hi:[0,1,1]
	v_pk_fma_f32 v[14:15], v[174:175], v[42:43], v[14:15] op_sel_hi:[0,1,1]
	v_fmac_f32_e32 v20, v174, v56
	s_waitcnt vmcnt(36)
	v_pk_fma_f32 v[10:11], v[176:177], v[24:25], v[10:11] op_sel_hi:[0,1,1]
	v_pk_fma_f32 v[12:13], v[176:177], v[32:33], v[12:13] op_sel_hi:[0,1,1]
	v_pk_fma_f32 v[16:17], v[176:177], v[40:41], v[16:17] op_sel_hi:[0,1,1]
	v_pk_fma_f32 v[14:15], v[176:177], v[48:49], v[14:15] op_sel_hi:[0,1,1]
	v_fmac_f32_e32 v20, v176, v57
	ds_read_b128 v[22:25], v5 offset:4096
	ds_read_b128 v[26:29], v5 offset:8192
	ds_read_b128 v[30:33], v5 offset:12288
	ds_read_b128 v[34:37], v5 offset:16384
	ds_read_b128 v[38:41], v5 offset:20480
	ds_read_b128 v[42:45], v5 offset:24576
	ds_read_b128 v[46:49], v5 offset:28672
	ds_read_b128 v[50:53], v5
	ds_read_b128 v[54:57], v5 offset:32768
	s_waitcnt lgkmcnt(8)
; DI void mod_item(const KP& P, int l, int nc, LAS float* S  , LAS float* red  ) {
;     ...
;         const float* w = P.w_mod + (size_t)l * D * 6144 + n0 + col;
; #pragma unroll 4
;         for (int k = kq * 128; k < kq * 128 + 128; ++k) { const float wv = w[(size_t)k * 6144];
; #pragma unroll
;             for (int r = 0; r < 9; ++r) a[r] += S[r * D + k] * wv; }
	v_mov_b32_e32 v67, v22
	v_add_u32_e32 v5, 16, v5
	s_waitcnt lgkmcnt(1)
	v_mov_b32_e32 v66, v50
	v_mov_b32_e32 v22, v51
	v_mov_b32_e32 v50, v52
	v_mov_b32_e32 v51, v24
	v_mov_b32_e32 v24, v53
	v_mov_b32_e32 v52, v26
	v_mov_b32_e32 v53, v30
	v_mov_b32_e32 v30, v27
	v_mov_b32_e32 v26, v28
	v_mov_b32_e32 v27, v32
	v_mov_b32_e32 v32, v29
	v_mov_b32_e32 v28, v34
	v_mov_b32_e32 v29, v38
	v_mov_b32_e32 v38, v35
	v_mov_b32_e32 v34, v36
	v_mov_b32_e32 v35, v40
	v_mov_b32_e32 v40, v37
	v_mov_b32_e32 v36, v42
	v_mov_b32_e32 v37, v46
	v_mov_b32_e32 v46, v43
	v_mov_b32_e32 v42, v44
	v_mov_b32_e32 v43, v48
	v_mov_b32_e32 v48, v45
	s_waitcnt vmcnt(35)
	v_pk_fma_f32 v[10:11], v[178:179], v[66:67], v[10:11] op_sel_hi:[0,1,1]
	v_pk_fma_f32 v[12:13], v[178:179], v[52:53], v[12:13] op_sel_hi:[0,1,1]
	v_pk_fma_f32 v[16:17], v[178:179], v[28:29], v[16:17] op_sel_hi:[0,1,1]
	v_pk_fma_f32 v[14:15], v[178:179], v[36:37], v[14:15] op_sel_hi:[0,1,1]
	s_waitcnt lgkmcnt(0)
	v_fmac_f32_e32 v20, v178, v54
	s_waitcnt vmcnt(34)
	v_pk_fma_f32 v[10:11], v[180:181], v[22:23], v[10:11] op_sel_hi:[0,1,1]
	v_pk_fma_f32 v[12:13], v[180:181], v[30:31], v[12:13] op_sel_hi:[0,1,1]
	v_pk_fma_f32 v[16:17], v[180:181], v[38:39], v[16:17] op_sel_hi:[0,1,1]
	v_pk_fma_f32 v[14:15], v[180:181], v[46:47], v[14:15] op_sel_hi:[0,1,1]
	v_fmac_f32_e32 v20, v180, v55
	s_waitcnt vmcnt(33)
	v_pk_fma_f32 v[10:11], v[182:183], v[50:51], v[10:11] op_sel_hi:[0,1,1]
	v_pk_fma_f32 v[12:13], v[182:183], v[26:27], v[12:13] op_sel_hi:[0,1,1]
	v_pk_fma_f32 v[16:17], v[182:183], v[34:35], v[16:17] op_sel_hi:[0,1,1]
	v_pk_fma_f32 v[14:15], v[182:183], v[42:43], v[14:15] op_sel_hi:[0,1,1]
	v_fmac_f32_e32 v20, v182, v56
	s_waitcnt vmcnt(32)
	v_pk_fma_f32 v[10:11], v[184:185], v[24:25], v[10:11] op_sel_hi:[0,1,1]
	v_pk_fma_f32 v[12:13], v[184:185], v[32:33], v[12:13] op_sel_hi:[0,1,1]
	v_pk_fma_f32 v[16:17], v[184:185], v[40:41], v[16:17] op_sel_hi:[0,1,1]
	v_pk_fma_f32 v[14:15], v[184:185], v[48:49], v[14:15] op_sel_hi:[0,1,1]
	v_fmac_f32_e32 v20, v184, v57
	ds_read_b128 v[22:25], v5 offset:4096
	ds_read_b128 v[26:29], v5 offset:8192
	ds_read_b128 v[30:33], v5 offset:12288
	ds_read_b128 v[34:37], v5 offset:16384
	ds_read_b128 v[38:41], v5 offset:20480
	ds_read_b128 v[42:45], v5 offset:24576
	ds_read_b128 v[46:49], v5 offset:28672
	ds_read_b128 v[50:53], v5
	ds_read_b128 v[54:57], v5 offset:32768
	s_waitcnt lgkmcnt(8)
	v_mov_b32_e32 v67, v22
	v_add_u32_e32 v5, 16, v5
	s_waitcnt lgkmcnt(1)
	v_mov_b32_e32 v66, v50
	v_mov_b32_e32 v22, v51
	v_mov_b32_e32 v50, v52
	v_mov_b32_e32 v51, v24
	v_mov_b32_e32 v24, v53
	v_mov_b32_e32 v52, v26
	v_mov_b32_e32 v53, v30
	v_mov_b32_e32 v30, v27
	v_mov_b32_e32 v26, v28
	v_mov_b32_e32 v27, v32
	v_mov_b32_e32 v32, v29
	v_mov_b32_e32 v28, v34
	v_mov_b32_e32 v29, v38
	v_mov_b32_e32 v38, v35
	v_mov_b32_e32 v34, v36
	v_mov_b32_e32 v35, v40
	v_mov_b32_e32 v40, v37
	v_mov_b32_e32 v36, v42
	v_mov_b32_e32 v37, v46
	v_mov_b32_e32 v46, v43
	v_mov_b32_e32 v42, v44
	v_mov_b32_e32 v43, v48
	v_mov_b32_e32 v48, v45
	s_waitcnt vmcnt(31)
	v_pk_fma_f32 v[10:11], v[186:187], v[66:67], v[10:11] op_sel_hi:[0,1,1]
	v_pk_fma_f32 v[12:13], v[186:187], v[52:53], v[12:13] op_sel_hi:[0,1,1]
	v_pk_fma_f32 v[16:17], v[186:187], v[28:29], v[16:17] op_sel_hi:[0,1,1]
	v_pk_fma_f32 v[14:15], v[186:187], v[36:37], v[14:15] op_sel_hi:[0,1,1]
	s_waitcnt lgkmcnt(0)
	v_fmac_f32_e32 v20, v186, v54
	s_waitcnt vmcnt(30)
	v_pk_fma_f32 v[10:11], v[188:189], v[22:23], v[10:11] op_sel_hi:[0,1,1]
	v_pk_fma_f32 v[12:13], v[188:189], v[30:31], v[12:13] op_sel_hi:[0,1,1]
	v_pk_fma_f32 v[16:17], v[188:189], v[38:39], v[16:17] op_sel_hi:[0,1,1]
	v_pk_fma_f32 v[14:15], v[188:189], v[46:47], v[14:15] op_sel_hi:[0,1,1]
	v_fmac_f32_e32 v20, v188, v55
	s_waitcnt vmcnt(29)
	v_pk_fma_f32 v[10:11], v[190:191], v[50:51], v[10:11] op_sel_hi:[0,1,1]
	v_pk_fma_f32 v[12:13], v[190:191], v[26:27], v[12:13] op_sel_hi:[0,1,1]
	v_pk_fma_f32 v[16:17], v[190:191], v[34:35], v[16:17] op_sel_hi:[0,1,1]
	v_pk_fma_f32 v[14:15], v[190:191], v[42:43], v[14:15] op_sel_hi:[0,1,1]
	v_fmac_f32_e32 v20, v190, v56
	s_waitcnt vmcnt(28)
	v_pk_fma_f32 v[10:11], v[192:193], v[24:25], v[10:11] op_sel_hi:[0,1,1]
	v_pk_fma_f32 v[12:13], v[192:193], v[32:33], v[12:13] op_sel_hi:[0,1,1]
	v_pk_fma_f32 v[16:17], v[192:193], v[40:41], v[16:17] op_sel_hi:[0,1,1]
	v_pk_fma_f32 v[14:15], v[192:193], v[48:49], v[14:15] op_sel_hi:[0,1,1]
	v_fmac_f32_e32 v20, v192, v57
	ds_read_b128 v[22:25], v5 offset:4096
	ds_read_b128 v[26:29], v5 offset:8192
	ds_read_b128 v[30:33], v5 offset:12288
	ds_read_b128 v[34:37], v5 offset:16384
	ds_read_b128 v[38:41], v5 offset:20480
	ds_read_b128 v[42:45], v5 offset:24576
	ds_read_b128 v[46:49], v5 offset:28672
	ds_read_b128 v[50:53], v5
	ds_read_b128 v[54:57], v5 offset:32768
	s_waitcnt lgkmcnt(8)
	v_mov_b32_e32 v67, v22
	v_add_u32_e32 v5, 16, v5
	s_waitcnt lgkmcnt(1)
	v_mov_b32_e32 v66, v50
	v_mov_b32_e32 v22, v51
	v_mov_b32_e32 v50, v52
	v_mov_b32_e32 v51, v24
	v_mov_b32_e32 v24, v53
	v_mov_b32_e32 v52, v26
	v_mov_b32_e32 v53, v30
	v_mov_b32_e32 v30, v27
	v_mov_b32_e32 v26, v28
	v_mov_b32_e32 v27, v32
	v_mov_b32_e32 v32, v29
	v_mov_b32_e32 v28, v34
	v_mov_b32_e32 v29, v38
	v_mov_b32_e32 v38, v35
	v_mov_b32_e32 v34, v36
	v_mov_b32_e32 v35, v40
	v_mov_b32_e32 v40, v37
	v_mov_b32_e32 v36, v42
	v_mov_b32_e32 v37, v46
	v_mov_b32_e32 v46, v43
	v_mov_b32_e32 v42, v44
	v_mov_b32_e32 v43, v48
	v_mov_b32_e32 v48, v45
	s_waitcnt vmcnt(27)
	v_pk_fma_f32 v[10:11], v[194:195], v[66:67], v[10:11] op_sel_hi:[0,1,1]
	v_pk_fma_f32 v[12:13], v[194:195], v[52:53], v[12:13] op_sel_hi:[0,1,1]
	v_pk_fma_f32 v[16:17], v[194:195], v[28:29], v[16:17] op_sel_hi:[0,1,1]
	v_pk_fma_f32 v[14:15], v[194:195], v[36:37], v[14:15] op_sel_hi:[0,1,1]
	s_waitcnt lgkmcnt(0)
; DI void mod_item(const KP& P, int l, int nc, LAS float* S  , LAS float* red  ) {
;     ...
;         const float* w = P.w_mod + (size_t)l * D * 6144 + n0 + col;
; #pragma unroll 4
;         for (int k = kq * 128; k < kq * 128 + 128; ++k) { const float wv = w[(size_t)k * 6144];
; #pragma unroll
;             for (int r = 0; r < 9; ++r) a[r] += S[r * D + k] * wv; }
	v_fmac_f32_e32 v20, v194, v54
	s_waitcnt vmcnt(26)
	v_pk_fma_f32 v[10:11], v[196:197], v[22:23], v[10:11] op_sel_hi:[0,1,1]
	v_pk_fma_f32 v[12:13], v[196:197], v[30:31], v[12:13] op_sel_hi:[0,1,1]
	v_pk_fma_f32 v[16:17], v[196:197], v[38:39], v[16:17] op_sel_hi:[0,1,1]
	v_pk_fma_f32 v[14:15], v[196:197], v[46:47], v[14:15] op_sel_hi:[0,1,1]
	v_fmac_f32_e32 v20, v196, v55
	s_waitcnt vmcnt(25)
	v_pk_fma_f32 v[10:11], v[198:199], v[50:51], v[10:11] op_sel_hi:[0,1,1]
	v_pk_fma_f32 v[12:13], v[198:199], v[26:27], v[12:13] op_sel_hi:[0,1,1]
	v_pk_fma_f32 v[16:17], v[198:199], v[34:35], v[16:17] op_sel_hi:[0,1,1]
	v_pk_fma_f32 v[14:15], v[198:199], v[42:43], v[14:15] op_sel_hi:[0,1,1]
	v_fmac_f32_e32 v20, v198, v56
	s_waitcnt vmcnt(24)
	v_pk_fma_f32 v[10:11], v[200:201], v[24:25], v[10:11] op_sel_hi:[0,1,1]
	v_pk_fma_f32 v[12:13], v[200:201], v[32:33], v[12:13] op_sel_hi:[0,1,1]
	v_pk_fma_f32 v[16:17], v[200:201], v[40:41], v[16:17] op_sel_hi:[0,1,1]
	v_pk_fma_f32 v[14:15], v[200:201], v[48:49], v[14:15] op_sel_hi:[0,1,1]
	v_fmac_f32_e32 v20, v200, v57
	ds_read_b128 v[22:25], v5 offset:4096
	ds_read_b128 v[26:29], v5 offset:8192
	ds_read_b128 v[30:33], v5 offset:12288
	ds_read_b128 v[34:37], v5 offset:16384
	ds_read_b128 v[38:41], v5 offset:20480
	ds_read_b128 v[42:45], v5 offset:24576
	ds_read_b128 v[46:49], v5 offset:28672
	ds_read_b128 v[50:53], v5
	ds_read_b128 v[54:57], v5 offset:32768
	s_waitcnt lgkmcnt(8)
	v_mov_b32_e32 v67, v22
	v_add_u32_e32 v5, 16, v5
	s_waitcnt lgkmcnt(1)
	v_mov_b32_e32 v66, v50
	v_mov_b32_e32 v22, v51
	v_mov_b32_e32 v50, v52
	v_mov_b32_e32 v51, v24
	v_mov_b32_e32 v24, v53
	v_mov_b32_e32 v52, v26
	v_mov_b32_e32 v53, v30
	v_mov_b32_e32 v30, v27
	v_mov_b32_e32 v26, v28
	v_mov_b32_e32 v27, v32
	v_mov_b32_e32 v32, v29
	v_mov_b32_e32 v28, v34
	v_mov_b32_e32 v29, v38
	v_mov_b32_e32 v38, v35
	v_mov_b32_e32 v34, v36
	v_mov_b32_e32 v35, v40
	v_mov_b32_e32 v40, v37
	v_mov_b32_e32 v36, v42
	v_mov_b32_e32 v37, v46
	v_mov_b32_e32 v46, v43
	v_mov_b32_e32 v42, v44
	v_mov_b32_e32 v43, v48
	v_mov_b32_e32 v48, v45
	s_waitcnt vmcnt(23)
	v_pk_fma_f32 v[10:11], v[202:203], v[66:67], v[10:11] op_sel_hi:[0,1,1]
	v_pk_fma_f32 v[12:13], v[202:203], v[52:53], v[12:13] op_sel_hi:[0,1,1]
	v_pk_fma_f32 v[16:17], v[202:203], v[28:29], v[16:17] op_sel_hi:[0,1,1]
	v_pk_fma_f32 v[14:15], v[202:203], v[36:37], v[14:15] op_sel_hi:[0,1,1]
	s_waitcnt lgkmcnt(0)
	v_fmac_f32_e32 v20, v202, v54
	s_waitcnt vmcnt(22)
	v_pk_fma_f32 v[10:11], v[204:205], v[22:23], v[10:11] op_sel_hi:[0,1,1]
	v_pk_fma_f32 v[12:13], v[204:205], v[30:31], v[12:13] op_sel_hi:[0,1,1]
	v_pk_fma_f32 v[16:17], v[204:205], v[38:39], v[16:17] op_sel_hi:[0,1,1]
	v_pk_fma_f32 v[14:15], v[204:205], v[46:47], v[14:15] op_sel_hi:[0,1,1]
	v_fmac_f32_e32 v20, v204, v55
	s_waitcnt vmcnt(21)
	v_pk_fma_f32 v[10:11], v[206:207], v[50:51], v[10:11] op_sel_hi:[0,1,1]
	v_pk_fma_f32 v[12:13], v[206:207], v[26:27], v[12:13] op_sel_hi:[0,1,1]
	v_pk_fma_f32 v[16:17], v[206:207], v[34:35], v[16:17] op_sel_hi:[0,1,1]
	v_pk_fma_f32 v[14:15], v[206:207], v[42:43], v[14:15] op_sel_hi:[0,1,1]
	v_fmac_f32_e32 v20, v206, v56
	s_waitcnt vmcnt(20)
	v_pk_fma_f32 v[10:11], v[208:209], v[24:25], v[10:11] op_sel_hi:[0,1,1]
	v_pk_fma_f32 v[12:13], v[208:209], v[32:33], v[12:13] op_sel_hi:[0,1,1]
	v_pk_fma_f32 v[16:17], v[208:209], v[40:41], v[16:17] op_sel_hi:[0,1,1]
	v_pk_fma_f32 v[14:15], v[208:209], v[48:49], v[14:15] op_sel_hi:[0,1,1]
	v_fmac_f32_e32 v20, v208, v57
	ds_read_b128 v[22:25], v5 offset:4096
	ds_read_b128 v[26:29], v5 offset:8192
	ds_read_b128 v[30:33], v5 offset:12288
	ds_read_b128 v[34:37], v5 offset:16384
	ds_read_b128 v[38:41], v5 offset:20480
	ds_read_b128 v[42:45], v5 offset:24576
	ds_read_b128 v[46:49], v5 offset:28672
	ds_read_b128 v[50:53], v5
	ds_read_b128 v[54:57], v5 offset:32768
	s_waitcnt lgkmcnt(8)
	v_mov_b32_e32 v67, v22
	v_add_u32_e32 v5, 16, v5
	s_waitcnt lgkmcnt(1)
	v_mov_b32_e32 v66, v50
	v_mov_b32_e32 v22, v51
	v_mov_b32_e32 v50, v52
	v_mov_b32_e32 v51, v24
	v_mov_b32_e32 v24, v53
	v_mov_b32_e32 v52, v26
	v_mov_b32_e32 v53, v30
	v_mov_b32_e32 v30, v27
	v_mov_b32_e32 v26, v28
	v_mov_b32_e32 v27, v32
	v_mov_b32_e32 v32, v29
	v_mov_b32_e32 v28, v34
	v_mov_b32_e32 v29, v38
	v_mov_b32_e32 v38, v35
	v_mov_b32_e32 v34, v36
	v_mov_b32_e32 v35, v40
	v_mov_b32_e32 v40, v37
	v_mov_b32_e32 v36, v42
	v_mov_b32_e32 v37, v46
	v_mov_b32_e32 v46, v43
	v_mov_b32_e32 v42, v44
	v_mov_b32_e32 v43, v48
	v_mov_b32_e32 v48, v45
	s_waitcnt vmcnt(19)
	v_pk_fma_f32 v[10:11], v[210:211], v[66:67], v[10:11] op_sel_hi:[0,1,1]
	v_pk_fma_f32 v[12:13], v[210:211], v[52:53], v[12:13] op_sel_hi:[0,1,1]
	v_pk_fma_f32 v[16:17], v[210:211], v[28:29], v[16:17] op_sel_hi:[0,1,1]
	v_pk_fma_f32 v[14:15], v[210:211], v[36:37], v[14:15] op_sel_hi:[0,1,1]
	s_waitcnt lgkmcnt(0)
	v_fmac_f32_e32 v20, v210, v54
	s_waitcnt vmcnt(18)
	v_pk_fma_f32 v[10:11], v[212:213], v[22:23], v[10:11] op_sel_hi:[0,1,1]
	v_pk_fma_f32 v[12:13], v[212:213], v[30:31], v[12:13] op_sel_hi:[0,1,1]
	v_pk_fma_f32 v[16:17], v[212:213], v[38:39], v[16:17] op_sel_hi:[0,1,1]
	v_pk_fma_f32 v[14:15], v[212:213], v[46:47], v[14:15] op_sel_hi:[0,1,1]
	v_fmac_f32_e32 v20, v212, v55
	s_waitcnt vmcnt(17)
	v_pk_fma_f32 v[10:11], v[214:215], v[50:51], v[10:11] op_sel_hi:[0,1,1]
	v_pk_fma_f32 v[12:13], v[214:215], v[26:27], v[12:13] op_sel_hi:[0,1,1]
	v_pk_fma_f32 v[16:17], v[214:215], v[34:35], v[16:17] op_sel_hi:[0,1,1]
	v_pk_fma_f32 v[14:15], v[214:215], v[42:43], v[14:15] op_sel_hi:[0,1,1]
	v_fmac_f32_e32 v20, v214, v56
	s_waitcnt vmcnt(16)
; DI void mod_item(const KP& P, int l, int nc, LAS float* S  , LAS float* red  ) {
;     ...
;         const float* w = P.w_mod + (size_t)l * D * 6144 + n0 + col;
; #pragma unroll 4
;         for (int k = kq * 128; k < kq * 128 + 128; ++k) { const float wv = w[(size_t)k * 6144];
; #pragma unroll
;             for (int r = 0; r < 9; ++r) a[r] += S[r * D + k] * wv; }
	v_pk_fma_f32 v[10:11], v[216:217], v[24:25], v[10:11] op_sel_hi:[0,1,1]
	v_pk_fma_f32 v[12:13], v[216:217], v[32:33], v[12:13] op_sel_hi:[0,1,1]
	v_pk_fma_f32 v[16:17], v[216:217], v[40:41], v[16:17] op_sel_hi:[0,1,1]
	v_pk_fma_f32 v[14:15], v[216:217], v[48:49], v[14:15] op_sel_hi:[0,1,1]
	v_fmac_f32_e32 v20, v216, v57
	ds_read_b128 v[22:25], v5 offset:4096
	ds_read_b128 v[26:29], v5 offset:8192
	ds_read_b128 v[30:33], v5 offset:12288
	ds_read_b128 v[34:37], v5 offset:16384
	ds_read_b128 v[38:41], v5 offset:20480
	ds_read_b128 v[42:45], v5 offset:24576
	ds_read_b128 v[46:49], v5 offset:28672
	ds_read_b128 v[50:53], v5
	ds_read_b128 v[54:57], v5 offset:32768
	s_waitcnt lgkmcnt(8)
	v_mov_b32_e32 v67, v22
	v_add_u32_e32 v5, 16, v5
	s_waitcnt lgkmcnt(1)
	v_mov_b32_e32 v66, v50
	v_mov_b32_e32 v22, v51
	v_mov_b32_e32 v50, v52
	v_mov_b32_e32 v51, v24
	v_mov_b32_e32 v24, v53
	v_mov_b32_e32 v52, v26
	v_mov_b32_e32 v53, v30
	v_mov_b32_e32 v30, v27
	v_mov_b32_e32 v26, v28
	v_mov_b32_e32 v27, v32
	v_mov_b32_e32 v32, v29
	v_mov_b32_e32 v28, v34
	v_mov_b32_e32 v29, v38
	v_mov_b32_e32 v38, v35
	v_mov_b32_e32 v34, v36
	v_mov_b32_e32 v35, v40
	v_mov_b32_e32 v40, v37
	v_mov_b32_e32 v36, v42
	v_mov_b32_e32 v37, v46
	v_mov_b32_e32 v46, v43
	v_mov_b32_e32 v42, v44
	v_mov_b32_e32 v43, v48
	v_mov_b32_e32 v48, v45
	s_waitcnt vmcnt(15)
	v_pk_fma_f32 v[10:11], v[218:219], v[66:67], v[10:11] op_sel_hi:[0,1,1]
	v_pk_fma_f32 v[12:13], v[218:219], v[52:53], v[12:13] op_sel_hi:[0,1,1]
	v_pk_fma_f32 v[16:17], v[218:219], v[28:29], v[16:17] op_sel_hi:[0,1,1]
	v_pk_fma_f32 v[14:15], v[218:219], v[36:37], v[14:15] op_sel_hi:[0,1,1]
	s_waitcnt lgkmcnt(0)
	v_fmac_f32_e32 v20, v218, v54
	s_waitcnt vmcnt(14)
	v_pk_fma_f32 v[10:11], v[220:221], v[22:23], v[10:11] op_sel_hi:[0,1,1]
	v_pk_fma_f32 v[12:13], v[220:221], v[30:31], v[12:13] op_sel_hi:[0,1,1]
	v_pk_fma_f32 v[16:17], v[220:221], v[38:39], v[16:17] op_sel_hi:[0,1,1]
	v_pk_fma_f32 v[14:15], v[220:221], v[46:47], v[14:15] op_sel_hi:[0,1,1]
	v_fmac_f32_e32 v20, v220, v55
	s_waitcnt vmcnt(13)
	v_pk_fma_f32 v[10:11], v[222:223], v[50:51], v[10:11] op_sel_hi:[0,1,1]
	v_pk_fma_f32 v[12:13], v[222:223], v[26:27], v[12:13] op_sel_hi:[0,1,1]
	v_pk_fma_f32 v[16:17], v[222:223], v[34:35], v[16:17] op_sel_hi:[0,1,1]
	v_pk_fma_f32 v[14:15], v[222:223], v[42:43], v[14:15] op_sel_hi:[0,1,1]
	v_fmac_f32_e32 v20, v222, v56
	s_waitcnt vmcnt(12)
	v_pk_fma_f32 v[10:11], v[224:225], v[24:25], v[10:11] op_sel_hi:[0,1,1]
	v_pk_fma_f32 v[12:13], v[224:225], v[32:33], v[12:13] op_sel_hi:[0,1,1]
	v_pk_fma_f32 v[16:17], v[224:225], v[40:41], v[16:17] op_sel_hi:[0,1,1]
	v_pk_fma_f32 v[14:15], v[224:225], v[48:49], v[14:15] op_sel_hi:[0,1,1]
	v_fmac_f32_e32 v20, v224, v57
	ds_read_b128 v[22:25], v5 offset:4096
	ds_read_b128 v[26:29], v5 offset:8192
	ds_read_b128 v[30:33], v5 offset:12288
	ds_read_b128 v[34:37], v5 offset:16384
	ds_read_b128 v[38:41], v5 offset:20480
	ds_read_b128 v[42:45], v5 offset:24576
	ds_read_b128 v[46:49], v5 offset:28672
	ds_read_b128 v[50:53], v5
	ds_read_b128 v[54:57], v5 offset:32768
	s_waitcnt lgkmcnt(8)
	v_mov_b32_e32 v67, v22
	v_add_u32_e32 v5, 16, v5
	s_waitcnt lgkmcnt(1)
	v_mov_b32_e32 v66, v50
	v_mov_b32_e32 v22, v51
	v_mov_b32_e32 v50, v52
	v_mov_b32_e32 v51, v24
	v_mov_b32_e32 v24, v53
	v_mov_b32_e32 v52, v26
	v_mov_b32_e32 v53, v30
	v_mov_b32_e32 v30, v27
	v_mov_b32_e32 v26, v28
	v_mov_b32_e32 v27, v32
	v_mov_b32_e32 v32, v29
	v_mov_b32_e32 v28, v34
	v_mov_b32_e32 v29, v38
	v_mov_b32_e32 v38, v35
	v_mov_b32_e32 v34, v36
	v_mov_b32_e32 v35, v40
	v_mov_b32_e32 v40, v37
	v_mov_b32_e32 v36, v42
	v_mov_b32_e32 v37, v46
	v_mov_b32_e32 v46, v43
	v_mov_b32_e32 v42, v44
	v_mov_b32_e32 v43, v48
	v_mov_b32_e32 v48, v45
	s_waitcnt vmcnt(11)
	v_pk_fma_f32 v[10:11], v[226:227], v[66:67], v[10:11] op_sel_hi:[0,1,1]
	v_pk_fma_f32 v[12:13], v[226:227], v[52:53], v[12:13] op_sel_hi:[0,1,1]
	v_pk_fma_f32 v[16:17], v[226:227], v[28:29], v[16:17] op_sel_hi:[0,1,1]
	v_pk_fma_f32 v[14:15], v[226:227], v[36:37], v[14:15] op_sel_hi:[0,1,1]
	s_waitcnt lgkmcnt(0)
	v_fmac_f32_e32 v20, v226, v54
	s_waitcnt vmcnt(10)
	v_pk_fma_f32 v[10:11], v[228:229], v[22:23], v[10:11] op_sel_hi:[0,1,1]
	v_pk_fma_f32 v[12:13], v[228:229], v[30:31], v[12:13] op_sel_hi:[0,1,1]
	v_pk_fma_f32 v[16:17], v[228:229], v[38:39], v[16:17] op_sel_hi:[0,1,1]
	v_pk_fma_f32 v[14:15], v[228:229], v[46:47], v[14:15] op_sel_hi:[0,1,1]
	v_fmac_f32_e32 v20, v228, v55
	s_waitcnt vmcnt(9)
	v_pk_fma_f32 v[10:11], v[230:231], v[50:51], v[10:11] op_sel_hi:[0,1,1]
	v_pk_fma_f32 v[12:13], v[230:231], v[26:27], v[12:13] op_sel_hi:[0,1,1]
	v_pk_fma_f32 v[16:17], v[230:231], v[34:35], v[16:17] op_sel_hi:[0,1,1]
	v_pk_fma_f32 v[14:15], v[230:231], v[42:43], v[14:15] op_sel_hi:[0,1,1]
	v_fmac_f32_e32 v20, v230, v56
	s_waitcnt vmcnt(8)
; DI void mod_item(const KP& P, int l, int nc, LAS float* S  , LAS float* red  ) {
;     ...
;         const float* w = P.w_mod + (size_t)l * D * 6144 + n0 + col;
; #pragma unroll 4
;         for (int k = kq * 128; k < kq * 128 + 128; ++k) { const float wv = w[(size_t)k * 6144];
; #pragma unroll
;             for (int r = 0; r < 9; ++r) a[r] += S[r * D + k] * wv; }
; #pragma unroll
;         for (int r = 0; r < 9; ++r) red[(kq * 9 + r) * 48 + col] = a[r];
	v_pk_fma_f32 v[10:11], v[232:233], v[24:25], v[10:11] op_sel_hi:[0,1,1]
	v_pk_fma_f32 v[12:13], v[232:233], v[32:33], v[12:13] op_sel_hi:[0,1,1]
	v_pk_fma_f32 v[16:17], v[232:233], v[40:41], v[16:17] op_sel_hi:[0,1,1]
	v_pk_fma_f32 v[14:15], v[232:233], v[48:49], v[14:15] op_sel_hi:[0,1,1]
	v_fmac_f32_e32 v20, v232, v57
	ds_read_b128 v[22:25], v5 offset:4096
	ds_read_b128 v[26:29], v5 offset:8192
	ds_read_b128 v[30:33], v5 offset:12288
	ds_read_b128 v[34:37], v5 offset:16384
	ds_read_b128 v[38:41], v5 offset:20480
	ds_read_b128 v[42:45], v5 offset:24576
	ds_read_b128 v[46:49], v5 offset:28672
	ds_read_b128 v[50:53], v5
	ds_read_b128 v[54:57], v5 offset:32768
	s_waitcnt lgkmcnt(8)
	v_mov_b32_e32 v67, v22
	v_add_u32_e32 v5, 16, v5
	s_waitcnt lgkmcnt(1)
	v_mov_b32_e32 v66, v50
	v_mov_b32_e32 v22, v51
	v_mov_b32_e32 v50, v52
	v_mov_b32_e32 v51, v24
	v_mov_b32_e32 v24, v53
	v_mov_b32_e32 v52, v26
	v_mov_b32_e32 v53, v30
	v_mov_b32_e32 v30, v27
	v_mov_b32_e32 v26, v28
	v_mov_b32_e32 v27, v32
	v_mov_b32_e32 v32, v29
	v_mov_b32_e32 v28, v34
	v_mov_b32_e32 v29, v38
	v_mov_b32_e32 v38, v35
	v_mov_b32_e32 v34, v36
	v_mov_b32_e32 v35, v40
	v_mov_b32_e32 v40, v37
	v_mov_b32_e32 v36, v42
	v_mov_b32_e32 v37, v46
	v_mov_b32_e32 v46, v43
	v_mov_b32_e32 v42, v44
	v_mov_b32_e32 v43, v48
	v_mov_b32_e32 v48, v45
	s_waitcnt vmcnt(7)
	v_pk_fma_f32 v[10:11], v[108:109], v[66:67], v[10:11] op_sel_hi:[0,1,1]
	v_pk_fma_f32 v[12:13], v[108:109], v[52:53], v[12:13] op_sel_hi:[0,1,1]
	v_pk_fma_f32 v[16:17], v[108:109], v[28:29], v[16:17] op_sel_hi:[0,1,1]
	v_pk_fma_f32 v[14:15], v[108:109], v[36:37], v[14:15] op_sel_hi:[0,1,1]
	s_waitcnt lgkmcnt(0)
	v_fmac_f32_e32 v20, v108, v54
	s_waitcnt vmcnt(6)
	v_pk_fma_f32 v[10:11], v[110:111], v[22:23], v[10:11] op_sel_hi:[0,1,1]
	v_pk_fma_f32 v[12:13], v[110:111], v[30:31], v[12:13] op_sel_hi:[0,1,1]
	v_pk_fma_f32 v[16:17], v[110:111], v[38:39], v[16:17] op_sel_hi:[0,1,1]
	v_pk_fma_f32 v[14:15], v[110:111], v[46:47], v[14:15] op_sel_hi:[0,1,1]
	v_fmac_f32_e32 v20, v110, v55
	s_waitcnt vmcnt(5)
	v_pk_fma_f32 v[10:11], v[112:113], v[50:51], v[10:11] op_sel_hi:[0,1,1]
	v_pk_fma_f32 v[12:13], v[112:113], v[26:27], v[12:13] op_sel_hi:[0,1,1]
	v_pk_fma_f32 v[16:17], v[112:113], v[34:35], v[16:17] op_sel_hi:[0,1,1]
	v_pk_fma_f32 v[14:15], v[112:113], v[42:43], v[14:15] op_sel_hi:[0,1,1]
	v_fmac_f32_e32 v20, v112, v56
	s_waitcnt vmcnt(4)
	v_pk_fma_f32 v[10:11], v[114:115], v[24:25], v[10:11] op_sel_hi:[0,1,1]
	v_pk_fma_f32 v[12:13], v[114:115], v[32:33], v[12:13] op_sel_hi:[0,1,1]
	v_pk_fma_f32 v[16:17], v[114:115], v[40:41], v[16:17] op_sel_hi:[0,1,1]
	v_pk_fma_f32 v[14:15], v[114:115], v[48:49], v[14:15] op_sel_hi:[0,1,1]
	v_fmac_f32_e32 v20, v114, v57
	ds_read_b128 v[22:25], v5 offset:4096
	ds_read_b128 v[26:29], v5 offset:8192
	ds_read_b128 v[30:33], v5 offset:12288
	ds_read_b128 v[34:37], v5 offset:16384
	ds_read_b128 v[38:41], v5 offset:20480
	ds_read_b128 v[42:45], v5 offset:24576
	ds_read_b128 v[46:49], v5 offset:28672
	ds_read_b128 v[50:53], v5
	ds_read_b128 v[54:57], v5 offset:32768
	s_waitcnt lgkmcnt(8)
	v_mov_b32_e32 v67, v22
	v_add_u32_e32 v5, 16, v5
	s_waitcnt lgkmcnt(1)
	v_mov_b32_e32 v66, v50
	v_mov_b32_e32 v22, v51
	v_mov_b32_e32 v50, v52
	v_mov_b32_e32 v51, v24
	v_mov_b32_e32 v24, v53
	v_mov_b32_e32 v52, v26
	v_mov_b32_e32 v53, v30
	v_mov_b32_e32 v30, v27
	v_mov_b32_e32 v26, v28
	v_mov_b32_e32 v27, v32
	v_mov_b32_e32 v32, v29
	v_mov_b32_e32 v28, v34
	v_mov_b32_e32 v29, v38
	v_mov_b32_e32 v38, v35
	v_mov_b32_e32 v34, v36
	v_mov_b32_e32 v35, v40
	v_mov_b32_e32 v40, v37
	v_mov_b32_e32 v36, v42
	v_mov_b32_e32 v37, v46
	v_mov_b32_e32 v46, v43
	v_mov_b32_e32 v42, v44
	v_mov_b32_e32 v43, v48
	v_mov_b32_e32 v48, v45
	s_waitcnt vmcnt(3)
	v_pk_fma_f32 v[10:11], v[116:117], v[66:67], v[10:11] op_sel_hi:[0,1,1]
	v_pk_fma_f32 v[12:13], v[116:117], v[52:53], v[12:13] op_sel_hi:[0,1,1]
	v_pk_fma_f32 v[16:17], v[116:117], v[28:29], v[16:17] op_sel_hi:[0,1,1]
	v_pk_fma_f32 v[14:15], v[116:117], v[36:37], v[14:15] op_sel_hi:[0,1,1]
	s_waitcnt lgkmcnt(0)
	v_fmac_f32_e32 v20, v116, v54
	s_waitcnt vmcnt(2)
	v_pk_fma_f32 v[10:11], v[118:119], v[22:23], v[10:11] op_sel_hi:[0,1,1]
	v_pk_fma_f32 v[12:13], v[118:119], v[30:31], v[12:13] op_sel_hi:[0,1,1]
	v_pk_fma_f32 v[16:17], v[118:119], v[38:39], v[16:17] op_sel_hi:[0,1,1]
	v_pk_fma_f32 v[14:15], v[118:119], v[46:47], v[14:15] op_sel_hi:[0,1,1]
	v_fmac_f32_e32 v20, v118, v55
	s_waitcnt vmcnt(1)
	v_pk_fma_f32 v[10:11], v[120:121], v[50:51], v[10:11] op_sel_hi:[0,1,1]
	v_pk_fma_f32 v[12:13], v[120:121], v[26:27], v[12:13] op_sel_hi:[0,1,1]
	v_pk_fma_f32 v[16:17], v[120:121], v[34:35], v[16:17] op_sel_hi:[0,1,1]
	v_pk_fma_f32 v[14:15], v[120:121], v[42:43], v[14:15] op_sel_hi:[0,1,1]
	v_fmac_f32_e32 v20, v120, v56
	s_waitcnt vmcnt(0)
	v_pk_fma_f32 v[10:11], v[122:123], v[24:25], v[10:11] op_sel_hi:[0,1,1]
	v_pk_fma_f32 v[12:13], v[122:123], v[32:33], v[12:13] op_sel_hi:[0,1,1]
	v_pk_fma_f32 v[16:17], v[122:123], v[40:41], v[16:17] op_sel_hi:[0,1,1]
	v_pk_fma_f32 v[14:15], v[122:123], v[48:49], v[14:15] op_sel_hi:[0,1,1]
	v_fmac_f32_e32 v20, v122, v57
	v_lshlrev_b32_e32 v5, 2, v6
	v_mul_lo_u32 v8, v2, s41
	v_add3_u32 v5, 0, v5, v8
	v_add_u32_e32 v8, 0x9000, v5
	ds_write2_b32 v8, v10, v11 offset1:48
	ds_write2_b32 v8, v12, v13 offset0:96 offset1:144
	ds_write2_b32 v8, v16, v17 offset0:192 offset1:240
	v_add_u32_e32 v8, 0x9400, v5
	ds_write2_b32 v8, v14, v15 offset0:32 offset1:80
	ds_write_b32 v5, v20 offset:38400
